# score-loop batching kept only for the sliding-window items (memory-attention score loops back to hipcc's form), P.V hoisting everywhere
# baseline (speedup 1.0000x reference)
.LBB0_151:
	s_or_b64 exec, exec, s[10:11]
	v_and_b32_e32 v5, 64, v229
	v_mov_b32_e32 v1, v4
	v_xor_b32_e32 v4, 16, v229
	v_add_u32_e32 v5, 64, v5
	v_cmp_lt_i32_e32 vcc, v4, v5
	v_and_b32_e32 v71, 15, v52
	v_mad_u32_u24 v79, v71, s13, v72
	v_cndmask_b32_e32 v78, v229, v4, vcc
	v_xor_b32_e32 v4, 32, v229
	v_cmp_lt_i32_e32 vcc, v4, v5
	v_mov_b32_e32 v65, v6
	ds_read_b128 v[8:11], v79 offset:64
	v_cndmask_b32_e32 v73, v229, v4, vcc
	ds_read_b128 v[4:7], v79
	s_waitcnt lgkmcnt(0)
	v_mfma_f32_16x16x32_bf16 v[4:7], v[4:7], v[0:3], 0
	v_lshlrev_b32_e32 v73, 2, v73
	ds_read_b128 v[74:77], v79 offset:32320
	v_mfma_f32_16x16x32_bf16 v[60:63], v[8:11], v[64:67], v[4:7]
	ds_read_b128 v[8:11], v79 offset:2368
	s_nop 3
	ds_read_b128 v[4:7], v79 offset:2304
	s_waitcnt lgkmcnt(0)
	v_mfma_f32_16x16x32_bf16 v[4:7], v[4:7], v[0:3], 0
	v_mfma_f32_16x16x32_bf16 v[56:59], v[8:11], v[64:67], v[4:7]
	ds_read_b128 v[8:11], v79 offset:4672
	s_nop 5
	ds_read_b128 v[4:7], v79 offset:4608
	s_waitcnt lgkmcnt(0)
	v_mfma_f32_16x16x32_bf16 v[4:7], v[4:7], v[0:3], 0
	v_mfma_f32_16x16x32_bf16 v[52:55], v[8:11], v[64:67], v[4:7]
	ds_read_b128 v[8:11], v79 offset:6976
	s_nop 5
	ds_read_b128 v[4:7], v79 offset:6912
	s_waitcnt lgkmcnt(0)
	v_mfma_f32_16x16x32_bf16 v[4:7], v[4:7], v[0:3], 0
	v_mfma_f32_16x16x32_bf16 v[48:51], v[8:11], v[64:67], v[4:7]
	ds_read_b128 v[8:11], v79 offset:9280
	s_nop 5
	ds_read_b128 v[4:7], v79 offset:9216
	s_waitcnt lgkmcnt(0)
	v_mfma_f32_16x16x32_bf16 v[4:7], v[4:7], v[0:3], 0
	v_mfma_f32_16x16x32_bf16 v[44:47], v[8:11], v[64:67], v[4:7]
	ds_read_b128 v[8:11], v79 offset:11584
	s_nop 5
	ds_read_b128 v[4:7], v79 offset:11520
	s_waitcnt lgkmcnt(0)
	v_mfma_f32_16x16x32_bf16 v[4:7], v[4:7], v[0:3], 0
	v_mfma_f32_16x16x32_bf16 v[40:43], v[8:11], v[64:67], v[4:7]
	ds_read_b128 v[8:11], v79 offset:13888
	s_nop 5
	ds_read_b128 v[4:7], v79 offset:13824
	s_waitcnt lgkmcnt(0)
	v_mfma_f32_16x16x32_bf16 v[4:7], v[4:7], v[0:3], 0
	v_mfma_f32_16x16x32_bf16 v[36:39], v[8:11], v[64:67], v[4:7]
	ds_read_b128 v[8:11], v79 offset:16192
	s_nop 5
	ds_read_b128 v[4:7], v79 offset:16128
	s_waitcnt lgkmcnt(0)
	v_mfma_f32_16x16x32_bf16 v[4:7], v[4:7], v[0:3], 0
	v_mfma_f32_16x16x32_bf16 v[32:35], v[8:11], v[64:67], v[4:7]
	ds_read_b128 v[8:11], v79 offset:18496
	s_nop 5
	ds_read_b128 v[4:7], v79 offset:18432
	s_waitcnt lgkmcnt(0)
	v_mfma_f32_16x16x32_bf16 v[4:7], v[4:7], v[0:3], 0
	v_mfma_f32_16x16x32_bf16 v[28:31], v[8:11], v[64:67], v[4:7]
	ds_read_b128 v[8:11], v79 offset:20800
	s_nop 5
	ds_read_b128 v[4:7], v79 offset:20736
	s_waitcnt lgkmcnt(0)
	v_mfma_f32_16x16x32_bf16 v[4:7], v[4:7], v[0:3], 0
	v_mfma_f32_16x16x32_bf16 v[24:27], v[8:11], v[64:67], v[4:7]
	ds_read_b128 v[8:11], v79 offset:23104
	s_nop 5
	ds_read_b128 v[4:7], v79 offset:23040
	s_waitcnt lgkmcnt(0)
	v_mfma_f32_16x16x32_bf16 v[4:7], v[4:7], v[0:3], 0
	v_mfma_f32_16x16x32_bf16 v[20:23], v[8:11], v[64:67], v[4:7]
	ds_read_b128 v[8:11], v79 offset:25408
	s_nop 5
	ds_read_b128 v[4:7], v79 offset:25344
	s_waitcnt lgkmcnt(0)
	v_mfma_f32_16x16x32_bf16 v[4:7], v[4:7], v[0:3], 0
	v_mfma_f32_16x16x32_bf16 v[16:19], v[8:11], v[64:67], v[4:7]
	ds_read_b128 v[8:11], v79 offset:27712
	s_nop 5
	ds_read_b128 v[4:7], v79 offset:27648
	s_waitcnt lgkmcnt(0)
	v_mfma_f32_16x16x32_bf16 v[4:7], v[4:7], v[0:3], 0
	v_mfma_f32_16x16x32_bf16 v[12:15], v[8:11], v[64:67], v[4:7]
	ds_read_b128 v[8:11], v79 offset:30016
	s_nop 5
	ds_read_b128 v[4:7], v79 offset:29952
	s_waitcnt lgkmcnt(0)
	v_mfma_f32_16x16x32_bf16 v[4:7], v[4:7], v[0:3], 0
	v_mfma_f32_16x16x32_bf16 v[8:11], v[8:11], v[64:67], v[4:7]
	s_nop 6
	ds_read_b128 v[4:7], v79 offset:32256
	s_waitcnt lgkmcnt(0)
	v_mfma_f32_16x16x32_bf16 v[4:7], v[4:7], v[0:3], 0
	v_mfma_f32_16x16x32_bf16 v[4:7], v[74:77], v[64:67], v[4:7]
	ds_read_b128 v[74:77], v79 offset:34560
	s_waitcnt lgkmcnt(0)
	v_mfma_f32_16x16x32_bf16 v[0:3], v[74:77], v[0:3], 0
	ds_read_b128 v[74:77], v79 offset:34624
	s_waitcnt lgkmcnt(0)
	v_mfma_f32_16x16x32_bf16 v[0:3], v[74:77], v[64:67], v[0:3]
	v_mul_f32_e32 v64, 0x3e000000, v60
	v_mul_f32_e32 v65, 0x3e000000, v61
	s_mov_b32 s2, 0xff61b1e6
	v_max3_f32 v64, v64, s2, v65
	v_mul_f32_e32 v65, 0x3e000000, v62
	v_mul_f32_e32 v66, 0x3e000000, v63
	v_max3_f32 v64, v64, v65, v66
	v_mul_f32_e32 v65, 0x3e000000, v56
	v_mul_f32_e32 v66, 0x3e000000, v57
	v_max3_f32 v64, v64, v65, v66
	v_mul_f32_e32 v65, 0x3e000000, v58
	v_mul_f32_e32 v66, 0x3e000000, v59
	v_max3_f32 v64, v64, v65, v66
	v_mul_f32_e32 v65, 0x3e000000, v52
	v_mul_f32_e32 v66, 0x3e000000, v53
	v_max3_f32 v64, v64, v65, v66
	v_mul_f32_e32 v65, 0x3e000000, v54
	v_mul_f32_e32 v66, 0x3e000000, v55
	v_max3_f32 v64, v64, v65, v66
	v_mul_f32_e32 v65, 0x3e000000, v48
	v_mul_f32_e32 v66, 0x3e000000, v49
	v_max3_f32 v64, v64, v65, v66
	v_mul_f32_e32 v65, 0x3e000000, v50
	v_mul_f32_e32 v66, 0x3e000000, v51
	v_max3_f32 v64, v64, v65, v66
	v_mul_f32_e32 v65, 0x3e000000, v44
	v_mul_f32_e32 v66, 0x3e000000, v45
	v_max3_f32 v64, v64, v65, v66
	v_mul_f32_e32 v65, 0x3e000000, v46
	v_mul_f32_e32 v66, 0x3e000000, v47
	v_max3_f32 v64, v64, v65, v66
	v_mul_f32_e32 v65, 0x3e000000, v40
	v_mul_f32_e32 v66, 0x3e000000, v41
	v_max3_f32 v64, v64, v65, v66
	v_mul_f32_e32 v65, 0x3e000000, v42
	v_mul_f32_e32 v66, 0x3e000000, v43
	v_max3_f32 v64, v64, v65, v66
	v_mul_f32_e32 v65, 0x3e000000, v36
	v_mul_f32_e32 v66, 0x3e000000, v37
	v_max3_f32 v64, v64, v65, v66
	v_mul_f32_e32 v65, 0x3e000000, v38
	v_mul_f32_e32 v66, 0x3e000000, v39
	v_max3_f32 v64, v64, v65, v66
	v_mul_f32_e32 v65, 0x3e000000, v32
	v_mul_f32_e32 v66, 0x3e000000, v33
	v_max3_f32 v64, v64, v65, v66
	v_mul_f32_e32 v65, 0x3e000000, v34
	v_mul_f32_e32 v66, 0x3e000000, v35
	v_max3_f32 v64, v64, v65, v66
	v_mul_f32_e32 v65, 0x3e000000, v28
	v_mul_f32_e32 v66, 0x3e000000, v29
	v_max3_f32 v64, v64, v65, v66
	v_mul_f32_e32 v65, 0x3e000000, v30
	v_mul_f32_e32 v66, 0x3e000000, v31
	v_max3_f32 v64, v64, v65, v66
	v_mul_f32_e32 v65, 0x3e000000, v24
	v_mul_f32_e32 v66, 0x3e000000, v25
	v_max3_f32 v64, v64, v65, v66
	v_mul_f32_e32 v65, 0x3e000000, v26
	v_mul_f32_e32 v66, 0x3e000000, v27
	v_max3_f32 v64, v64, v65, v66
	v_mul_f32_e32 v65, 0x3e000000, v20
	v_mul_f32_e32 v66, 0x3e000000, v21
	v_max3_f32 v64, v64, v65, v66
	v_mul_f32_e32 v65, 0x3e000000, v22
	v_mul_f32_e32 v66, 0x3e000000, v23
	v_max3_f32 v64, v64, v65, v66
	v_mul_f32_e32 v65, 0x3e000000, v16
	v_mul_f32_e32 v66, 0x3e000000, v17
	v_max3_f32 v64, v64, v65, v66
	v_mul_f32_e32 v65, 0x3e000000, v18
	v_mul_f32_e32 v66, 0x3e000000, v19
	v_max3_f32 v64, v64, v65, v66
	v_mul_f32_e32 v65, 0x3e000000, v12
	v_mul_f32_e32 v66, 0x3e000000, v13
	v_max3_f32 v64, v64, v65, v66
	v_mul_f32_e32 v65, 0x3e000000, v14
	v_mul_f32_e32 v66, 0x3e000000, v15
	v_max3_f32 v64, v64, v65, v66
	v_mul_f32_e32 v65, 0x3e000000, v8
	v_mul_f32_e32 v66, 0x3e000000, v9
	v_max3_f32 v64, v64, v65, v66
	v_mul_f32_e32 v65, 0x3e000000, v10
	v_mul_f32_e32 v66, 0x3e000000, v11
	v_max3_f32 v64, v64, v65, v66
	v_mul_f32_e32 v65, 0x3e000000, v4
	v_mul_f32_e32 v66, 0x3e000000, v5
	v_max3_f32 v64, v64, v65, v66
	v_mul_f32_e32 v65, 0x3e000000, v6
	v_mul_f32_e32 v66, 0x3e000000, v7
	v_max3_f32 v64, v64, v65, v66
	v_mul_f32_e32 v65, 0x3e000000, v0
	v_mul_f32_e32 v66, 0x3e000000, v1
	v_max3_f32 v64, v64, v65, v66
	v_mul_f32_e32 v65, 0x3e000000, v2
	v_mul_f32_e32 v66, 0x3e000000, v3
	v_max3_f32 v64, v64, v65, v66
	v_lshlrev_b32_e32 v74, 2, v78
	ds_bpermute_b32 v65, v74, v64
	s_mov_b32 s2, 0x3e000000
	v_sub_u32_e32 v72, v72, v70
	s_waitcnt lgkmcnt(0)
	v_max_f32_e32 v65, v65, v65
	v_max_f32_e32 v64, v64, v65
	ds_bpermute_b32 v65, v73, v64
	s_waitcnt lgkmcnt(0)
	v_max_f32_e32 v65, v65, v65
	v_max_f32_e32 v75, v64, v65
	v_fma_f32 v60, v60, s2, -v75
	v_fma_f32 v61, v61, s2, -v75
	v_mul_f32_e32 v60, 0x3fb8aa3b, v60
	v_mul_f32_e32 v61, 0x3fb8aa3b, v61
	v_exp_f32_e32 v60, v60
	v_exp_f32_e32 v64, v61
	v_fma_f32 v61, v62, s2, -v75
	v_mul_f32_e32 v61, 0x3fb8aa3b, v61
	v_exp_f32_e32 v61, v61
	v_add_f32_e32 v65, 0, v60
	v_fma_f32 v63, v63, s2, -v75
	v_add_f32_e32 v65, v64, v65
	v_mul_f32_e32 v63, 0x3fb8aa3b, v63
	v_add_f32_e32 v62, v61, v65
	v_exp_f32_e32 v65, v63
	v_fma_f32 v56, v56, s2, -v75
	v_mul_f32_e32 v56, 0x3fb8aa3b, v56
	v_fma_f32 v57, v57, s2, -v75
	v_add_f32_e32 v63, v65, v62
	v_exp_f32_e32 v62, v56
	v_mul_f32_e32 v57, 0x3fb8aa3b, v57
	v_exp_f32_e32 v66, v57
	v_fma_f32 v57, v58, s2, -v75
	v_mul_f32_e32 v57, 0x3fb8aa3b, v57
	v_add_f32_e32 v56, v62, v63
	v_exp_f32_e32 v63, v57
	v_fma_f32 v57, v59, s2, -v75
	v_mul_f32_e32 v57, 0x3fb8aa3b, v57
	v_fma_f32 v52, v52, s2, -v75
	v_exp_f32_e32 v67, v57
	v_mul_f32_e32 v52, 0x3fb8aa3b, v52
	v_exp_f32_e32 v52, v52
	v_add_f32_e32 v56, v66, v56
	v_add_f32_e32 v56, v63, v56
	v_fma_f32 v53, v53, s2, -v75
	v_add_f32_e32 v56, v67, v56
	v_mul_f32_e32 v53, 0x3fb8aa3b, v53
	v_add_f32_e32 v57, v52, v56
	v_exp_f32_e32 v56, v53
	v_fma_f32 v53, v54, s2, -v75
	v_mul_f32_e32 v53, 0x3fb8aa3b, v53
	v_exp_f32_e32 v53, v53
	v_fma_f32 v55, v55, s2, -v75
	v_add_f32_e32 v57, v56, v57
	v_mul_f32_e32 v55, 0x3fb8aa3b, v55
	v_add_f32_e32 v54, v53, v57
	v_exp_f32_e32 v57, v55
	v_fma_f32 v48, v48, s2, -v75
	v_mul_f32_e32 v48, 0x3fb8aa3b, v48
	v_fma_f32 v49, v49, s2, -v75
	v_add_f32_e32 v55, v57, v54
	v_exp_f32_e32 v54, v48
	v_mul_f32_e32 v49, 0x3fb8aa3b, v49
	v_exp_f32_e32 v58, v49
	v_fma_f32 v49, v50, s2, -v75
	v_mul_f32_e32 v49, 0x3fb8aa3b, v49
	v_add_f32_e32 v48, v54, v55
	v_exp_f32_e32 v55, v49
	v_fma_f32 v49, v51, s2, -v75
	v_mul_f32_e32 v49, 0x3fb8aa3b, v49
	v_fma_f32 v44, v44, s2, -v75
	v_exp_f32_e32 v59, v49
	v_mul_f32_e32 v44, 0x3fb8aa3b, v44
	v_exp_f32_e32 v44, v44
	v_add_f32_e32 v48, v58, v48
	v_add_f32_e32 v48, v55, v48
	v_fma_f32 v45, v45, s2, -v75
	v_add_f32_e32 v48, v59, v48
	v_mul_f32_e32 v45, 0x3fb8aa3b, v45
	v_add_f32_e32 v49, v44, v48
	v_exp_f32_e32 v48, v45
	v_fma_f32 v45, v46, s2, -v75
	v_mul_f32_e32 v45, 0x3fb8aa3b, v45
	v_exp_f32_e32 v45, v45
	v_fma_f32 v47, v47, s2, -v75
	v_add_f32_e32 v49, v48, v49
	v_mul_f32_e32 v47, 0x3fb8aa3b, v47
	v_add_f32_e32 v46, v45, v49
	v_exp_f32_e32 v49, v47
	v_fma_f32 v40, v40, s2, -v75
	v_mul_f32_e32 v40, 0x3fb8aa3b, v40
	v_fma_f32 v41, v41, s2, -v75
	v_add_f32_e32 v47, v49, v46
	v_exp_f32_e32 v46, v40
	v_mul_f32_e32 v41, 0x3fb8aa3b, v41
	v_exp_f32_e32 v50, v41
	v_fma_f32 v41, v42, s2, -v75
	v_mul_f32_e32 v41, 0x3fb8aa3b, v41
	v_add_f32_e32 v40, v46, v47
	v_exp_f32_e32 v47, v41
	v_fma_f32 v41, v43, s2, -v75
	v_mul_f32_e32 v41, 0x3fb8aa3b, v41
	v_fma_f32 v36, v36, s2, -v75
	v_exp_f32_e32 v51, v41
	v_mul_f32_e32 v36, 0x3fb8aa3b, v36
	v_exp_f32_e32 v36, v36
	v_add_f32_e32 v40, v50, v40
	v_add_f32_e32 v40, v47, v40
	v_fma_f32 v37, v37, s2, -v75
	v_add_f32_e32 v40, v51, v40
	v_mul_f32_e32 v37, 0x3fb8aa3b, v37
	v_add_f32_e32 v41, v36, v40
	v_exp_f32_e32 v40, v37
	v_fma_f32 v37, v38, s2, -v75
	v_mul_f32_e32 v37, 0x3fb8aa3b, v37
	v_exp_f32_e32 v37, v37
	v_fma_f32 v39, v39, s2, -v75
	v_add_f32_e32 v41, v40, v41
	v_mul_f32_e32 v39, 0x3fb8aa3b, v39
	v_add_f32_e32 v38, v37, v41
	v_exp_f32_e32 v41, v39
	v_fma_f32 v32, v32, s2, -v75
	v_mul_f32_e32 v32, 0x3fb8aa3b, v32
	v_fma_f32 v33, v33, s2, -v75
	v_add_f32_e32 v39, v41, v38
	v_exp_f32_e32 v38, v32
	v_mul_f32_e32 v33, 0x3fb8aa3b, v33
	v_exp_f32_e32 v42, v33
	v_fma_f32 v33, v34, s2, -v75
	v_mul_f32_e32 v33, 0x3fb8aa3b, v33
	v_add_f32_e32 v32, v38, v39
	v_exp_f32_e32 v39, v33
	v_fma_f32 v33, v35, s2, -v75
	v_mul_f32_e32 v33, 0x3fb8aa3b, v33
	v_fma_f32 v28, v28, s2, -v75
	v_exp_f32_e32 v43, v33
	v_mul_f32_e32 v28, 0x3fb8aa3b, v28
	v_exp_f32_e32 v28, v28
	v_add_f32_e32 v32, v42, v32
	v_add_f32_e32 v32, v39, v32
	v_fma_f32 v29, v29, s2, -v75
	v_add_f32_e32 v32, v43, v32
	v_mul_f32_e32 v29, 0x3fb8aa3b, v29
	v_add_f32_e32 v33, v28, v32
	v_exp_f32_e32 v32, v29
	v_fma_f32 v29, v30, s2, -v75
	v_mul_f32_e32 v29, 0x3fb8aa3b, v29
	v_exp_f32_e32 v29, v29
	v_fma_f32 v31, v31, s2, -v75
	v_add_f32_e32 v33, v32, v33
	v_mul_f32_e32 v31, 0x3fb8aa3b, v31
	v_add_f32_e32 v30, v29, v33
	v_exp_f32_e32 v33, v31
	v_fma_f32 v24, v24, s2, -v75
	v_mul_f32_e32 v24, 0x3fb8aa3b, v24
	v_fma_f32 v25, v25, s2, -v75
	v_add_f32_e32 v31, v33, v30
	v_exp_f32_e32 v30, v24
	v_mul_f32_e32 v25, 0x3fb8aa3b, v25
	v_exp_f32_e32 v34, v25
	v_fma_f32 v25, v26, s2, -v75
	v_mul_f32_e32 v25, 0x3fb8aa3b, v25
	v_add_f32_e32 v24, v30, v31
	v_exp_f32_e32 v31, v25
	v_fma_f32 v25, v27, s2, -v75
	v_mul_f32_e32 v25, 0x3fb8aa3b, v25
	v_fma_f32 v20, v20, s2, -v75
	v_exp_f32_e32 v35, v25
	v_mul_f32_e32 v20, 0x3fb8aa3b, v20
	v_exp_f32_e32 v20, v20
	v_add_f32_e32 v24, v34, v24
	v_add_f32_e32 v24, v31, v24
	v_fma_f32 v21, v21, s2, -v75
	v_add_f32_e32 v24, v35, v24
	v_mul_f32_e32 v21, 0x3fb8aa3b, v21
	v_add_f32_e32 v25, v20, v24
	v_exp_f32_e32 v24, v21
	v_fma_f32 v21, v22, s2, -v75
	v_mul_f32_e32 v21, 0x3fb8aa3b, v21
	v_exp_f32_e32 v21, v21
	v_fma_f32 v23, v23, s2, -v75
	v_add_f32_e32 v25, v24, v25
	v_mul_f32_e32 v23, 0x3fb8aa3b, v23
	v_add_f32_e32 v22, v21, v25
	v_exp_f32_e32 v25, v23
	v_fma_f32 v16, v16, s2, -v75
	v_mul_f32_e32 v16, 0x3fb8aa3b, v16
	v_fma_f32 v17, v17, s2, -v75
	v_add_f32_e32 v23, v25, v22
	v_exp_f32_e32 v22, v16
	v_mul_f32_e32 v17, 0x3fb8aa3b, v17
	v_exp_f32_e32 v26, v17
	v_fma_f32 v17, v18, s2, -v75
	v_mul_f32_e32 v17, 0x3fb8aa3b, v17
	v_add_f32_e32 v16, v22, v23
	v_exp_f32_e32 v23, v17
	v_fma_f32 v17, v19, s2, -v75
	v_mul_f32_e32 v17, 0x3fb8aa3b, v17
	v_fma_f32 v12, v12, s2, -v75
	v_exp_f32_e32 v27, v17
	v_mul_f32_e32 v12, 0x3fb8aa3b, v12
	v_exp_f32_e32 v12, v12
	v_add_f32_e32 v16, v26, v16
	v_add_f32_e32 v16, v23, v16
	v_fma_f32 v13, v13, s2, -v75
	v_add_f32_e32 v16, v27, v16
	v_mul_f32_e32 v13, 0x3fb8aa3b, v13
	v_add_f32_e32 v17, v12, v16
	v_exp_f32_e32 v16, v13
	v_fma_f32 v13, v14, s2, -v75
	v_mul_f32_e32 v13, 0x3fb8aa3b, v13
	v_exp_f32_e32 v13, v13
	v_fma_f32 v15, v15, s2, -v75
	v_add_f32_e32 v17, v16, v17
	v_mul_f32_e32 v15, 0x3fb8aa3b, v15
	v_add_f32_e32 v14, v13, v17
	v_exp_f32_e32 v17, v15
	v_fma_f32 v8, v8, s2, -v75
	v_mul_f32_e32 v8, 0x3fb8aa3b, v8
	v_fma_f32 v9, v9, s2, -v75
	v_add_f32_e32 v15, v17, v14
	v_exp_f32_e32 v14, v8
	v_mul_f32_e32 v9, 0x3fb8aa3b, v9
	v_exp_f32_e32 v18, v9
	v_fma_f32 v9, v10, s2, -v75
	v_mul_f32_e32 v9, 0x3fb8aa3b, v9
	v_add_f32_e32 v8, v14, v15
	v_exp_f32_e32 v15, v9
	v_fma_f32 v9, v11, s2, -v75
	v_mul_f32_e32 v9, 0x3fb8aa3b, v9
	v_fma_f32 v4, v4, s2, -v75
	v_exp_f32_e32 v19, v9
	v_mul_f32_e32 v4, 0x3fb8aa3b, v4
	v_exp_f32_e32 v4, v4
	v_add_f32_e32 v8, v18, v8
	v_add_f32_e32 v8, v15, v8
	v_fma_f32 v5, v5, s2, -v75
	v_add_f32_e32 v8, v19, v8
	v_mul_f32_e32 v5, 0x3fb8aa3b, v5
	v_add_f32_e32 v9, v4, v8
	v_exp_f32_e32 v8, v5
	v_fma_f32 v5, v6, s2, -v75
	v_mul_f32_e32 v5, 0x3fb8aa3b, v5
	v_exp_f32_e32 v5, v5
	v_fma_f32 v7, v7, s2, -v75
	v_add_f32_e32 v9, v8, v9
	v_mul_f32_e32 v7, 0x3fb8aa3b, v7
	v_fma_f32 v0, v0, s2, -v75
	v_add_f32_e32 v6, v5, v9
	v_exp_f32_e32 v9, v7
	v_mul_f32_e32 v0, 0x3fb8aa3b, v0
	v_exp_f32_e32 v0, v0
	v_fma_f32 v1, v1, s2, -v75
	v_add_f32_e32 v6, v9, v6
	v_mul_f32_e32 v1, 0x3fb8aa3b, v1
	v_add_f32_e32 v7, v0, v6
	v_exp_f32_e32 v6, v1
	v_fma_f32 v1, v2, s2, -v75
	v_mul_f32_e32 v1, 0x3fb8aa3b, v1
	v_exp_f32_e32 v1, v1
	v_fma_f32 v3, v3, s2, -v75
	v_add_f32_e32 v7, v6, v7
	v_mul_f32_e32 v3, 0x3fb8aa3b, v3
	v_add_f32_e32 v2, v1, v7
	v_exp_f32_e32 v7, v3
	s_nop 0
	v_add_f32_e32 v2, v7, v2
	ds_bpermute_b32 v3, v74, v2
	s_waitcnt lgkmcnt(0)
	v_add_f32_e32 v2, v2, v3
	ds_bpermute_b32 v3, v73, v2
	s_waitcnt lgkmcnt(0)
	v_add_f32_e32 v2, v2, v3
	v_div_scale_f32 v3, s[2:3], v2, v2, 1.0
	v_rcp_f32_e32 v10, v3
	v_div_scale_f32 v11, vcc, 1.0, v2, 1.0
	s_movk_i32 s2, 0x210
	v_fma_f32 v73, -v3, v10, 1.0
	v_fmac_f32_e32 v10, v73, v10
	v_mul_f32_e32 v73, v11, v10
	v_fma_f32 v74, -v3, v73, v11
	v_fmac_f32_e32 v73, v74, v10
	v_fma_f32 v3, -v3, v73, v11
	v_div_fmas_f32 v3, v3, v10, v73
	v_div_fixup_f32 v2, v3, v2, 1.0
	v_pk_mul_f32 v[10:11], v[60:61], v[2:3] op_sel_hi:[1,0]
	v_pk_mul_f32 v[60:61], v[64:65], v[2:3] op_sel_hi:[1,0]
	v_pk_mul_f32 v[64:65], v[66:67], v[2:3] op_sel_hi:[1,0]
	v_pk_mul_f32 v[62:63], v[62:63], v[2:3] op_sel_hi:[1,0]
	v_bfe_u32 v3, v65, 16, 1
	v_bfe_u32 v66, v64, 16, 1
	v_bfe_u32 v67, v61, 16, 1
	v_bfe_u32 v73, v60, 16, 1
	v_add3_u32 v65, v65, v3, s33
	v_bfe_u32 v3, v10, 16, 1
	v_mad_u32_u24 v71, v71, s2, v72
	v_add3_u32 v73, v60, v73, s33
	v_add3_u32 v74, v61, v67, s33
	v_add3_u32 v64, v64, v66, s33
	v_bfe_u32 v60, v11, 16, 1
	v_bfe_u32 v61, v62, 16, 1
	v_bfe_u32 v66, v63, 16, 1
	v_add3_u32 v10, v10, v3, s33
	v_add_u32_e32 v3, 0x9000, v71
	v_add3_u32 v66, v63, v66, s33
	v_add3_u32 v67, v62, v61, s33
	v_add3_u32 v11, v11, v60, s33
	ds_read2_b64 v[60:63], v3 offset1:4
	v_lshrrev_b32_e32 v10, 16, v10
	v_lshrrev_b32_e32 v11, 16, v11
	v_lshrrev_b32_e32 v72, 16, v67
	v_lshrrev_b32_e32 v66, 16, v66
	v_and_or_b32 v67, v65, s29, v66
	v_and_or_b32 v66, v64, s29, v72
	v_and_or_b32 v65, v74, s29, v11
	v_and_or_b32 v64, v73, s29, v10
	v_add_u32_e32 v10, 0xb000, v71
	s_waitcnt lgkmcnt(0)
	v_mfma_f32_16x16x32_bf16 v[72:75], v[60:63], v[64:67], 0
	ds_read2_b64 v[60:63], v10 offset0:32 offset1:36
	s_waitcnt lgkmcnt(0)
	v_mfma_f32_16x16x32_bf16 v[76:79], v[60:63], v[64:67], 0
	v_add_u32_e32 v60, 0xd000, v71
	v_add_u32_e32 v61, 0xf000, v71
	ds_read2_b64 v[82:85], v60 offset0:64 offset1:68
	ds_read2_b64 v[86:89], v61 offset0:96 offset1:100
	s_waitcnt lgkmcnt(1)
	v_mfma_f32_16x16x32_bf16 v[82:85], v[82:85], v[64:67], 0
	s_waitcnt lgkmcnt(0)
	v_mfma_f32_16x16x32_bf16 v[62:65], v[86:89], v[64:67], 0
	ds_read2_b64 v[116:119], v3 offset0:8 offset1:12
	ds_read2_b64 v[120:123], v10 offset0:40 offset1:44
	ds_read2_b64 v[124:127], v60 offset0:72 offset1:76
	ds_read2_b64 v[128:131], v61 offset0:104 offset1:108
	v_mul_f32_e64 v56, v56, v2
	v_mul_f32_e64 v57, v57, v2
	v_pk_mul_f32 v[58:59], v[58:59], v[2:3] op_sel_hi:[1,0]
	v_pk_mul_f32 v[52:53], v[52:53], v[2:3] op_sel_hi:[1,0]
	v_pk_mul_f32 v[54:55], v[54:55], v[2:3] op_sel_hi:[1,0]
	v_bfe_u32 v11, v59, 16, 1
	v_bfe_u32 v66, v58, 16, 1
	v_bfe_u32 v67, v57, 16, 1
	v_bfe_u32 v71, v56, 16, 1
	v_add3_u32 v56, v56, v71, s33
	v_add3_u32 v57, v57, v67, s33
	v_add3_u32 v58, v58, v66, s33
	v_add3_u32 v11, v59, v11, s33
	v_bfe_u32 v59, v52, 16, 1
	v_bfe_u32 v66, v53, 16, 1
	v_bfe_u32 v67, v54, 16, 1
	v_bfe_u32 v71, v55, 16, 1
	v_add3_u32 v71, v55, v71, s33
	v_add3_u32 v67, v54, v67, s33
	v_add3_u32 v66, v53, v66, s33
	v_add3_u32 v59, v52, v59, s33
	v_lshrrev_b32_e32 v81, 16, v59
	v_lshrrev_b32_e32 v66, 16, v66
	v_lshrrev_b32_e32 v67, 16, v67
	v_lshrrev_b32_e32 v59, 16, v71
	v_and_or_b32 v59, v11, s29, v59
	v_and_or_b32 v58, v58, s29, v67
	v_and_or_b32 v57, v57, s29, v66
	v_and_or_b32 v56, v56, s29, v81
	s_waitcnt lgkmcnt(3)
	s_nop 1
	v_mfma_f32_16x16x32_bf16 v[52:55], v[116:119], v[56:59], v[72:75]
	s_waitcnt lgkmcnt(2)
	v_mfma_f32_16x16x32_bf16 v[72:75], v[120:123], v[56:59], v[76:79]
	s_waitcnt lgkmcnt(1)
	v_mfma_f32_16x16x32_bf16 v[76:79], v[124:127], v[56:59], v[82:85]
	s_waitcnt lgkmcnt(0)
	v_mfma_f32_16x16x32_bf16 v[56:59], v[128:131], v[56:59], v[62:65]
	ds_read2_b64 v[132:135], v3 offset0:16 offset1:20
	ds_read2_b64 v[136:139], v10 offset0:48 offset1:52
	ds_read2_b64 v[140:143], v60 offset0:80 offset1:84
	ds_read2_b64 v[144:147], v61 offset0:112 offset1:116
	v_mul_f32_e64 v48, v48, v2
	v_mul_f32_e64 v49, v49, v2
	v_pk_mul_f32 v[50:51], v[50:51], v[2:3] op_sel_hi:[1,0]
	v_pk_mul_f32 v[44:45], v[44:45], v[2:3] op_sel_hi:[1,0]
	v_pk_mul_f32 v[46:47], v[46:47], v[2:3] op_sel_hi:[1,0]
	v_bfe_u32 v11, v51, 16, 1
	v_bfe_u32 v62, v50, 16, 1
	v_bfe_u32 v63, v49, 16, 1
	v_bfe_u32 v64, v48, 16, 1
	v_add3_u32 v48, v48, v64, s33
	v_add3_u32 v49, v49, v63, s33
	v_add3_u32 v50, v50, v62, s33
	v_add3_u32 v11, v51, v11, s33
	v_bfe_u32 v51, v44, 16, 1
	v_bfe_u32 v62, v45, 16, 1
	v_bfe_u32 v63, v46, 16, 1
	v_bfe_u32 v64, v47, 16, 1
	v_add3_u32 v64, v47, v64, s33
	v_add3_u32 v63, v46, v63, s33
	v_add3_u32 v62, v45, v62, s33
	v_add3_u32 v51, v44, v51, s33
	v_lshrrev_b32_e32 v65, 16, v51
	v_lshrrev_b32_e32 v62, 16, v62
	v_lshrrev_b32_e32 v63, 16, v63
	v_lshrrev_b32_e32 v51, 16, v64
	v_and_or_b32 v51, v11, s29, v51
	v_and_or_b32 v50, v50, s29, v63
	v_and_or_b32 v49, v49, s29, v62
	v_and_or_b32 v48, v48, s29, v65
	s_waitcnt lgkmcnt(3)
	s_nop 1
	v_mfma_f32_16x16x32_bf16 v[44:47], v[132:135], v[48:51], v[52:55]
	s_waitcnt lgkmcnt(2)
	v_mfma_f32_16x16x32_bf16 v[52:55], v[136:139], v[48:51], v[72:75]
	s_waitcnt lgkmcnt(1)
	v_mfma_f32_16x16x32_bf16 v[62:65], v[140:143], v[48:51], v[76:79]
	s_waitcnt lgkmcnt(0)
	v_mfma_f32_16x16x32_bf16 v[48:51], v[144:147], v[48:51], v[56:59]
	ds_read2_b64 v[116:119], v3 offset0:24 offset1:28
	ds_read2_b64 v[120:123], v10 offset0:56 offset1:60
	ds_read2_b64 v[124:127], v60 offset0:88 offset1:92
	ds_read2_b64 v[128:131], v61 offset0:120 offset1:124
	v_mul_f32_e64 v40, v40, v2
	v_mul_f32_e64 v41, v41, v2
	v_pk_mul_f32 v[42:43], v[42:43], v[2:3] op_sel_hi:[1,0]
	v_pk_mul_f32 v[36:37], v[36:37], v[2:3] op_sel_hi:[1,0]
	v_pk_mul_f32 v[38:39], v[38:39], v[2:3] op_sel_hi:[1,0]
	v_bfe_u32 v11, v43, 16, 1
	v_bfe_u32 v56, v42, 16, 1
	v_bfe_u32 v57, v41, 16, 1
	v_bfe_u32 v58, v40, 16, 1
	v_add3_u32 v40, v40, v58, s33
	v_add3_u32 v41, v41, v57, s33
	v_add3_u32 v42, v42, v56, s33
	v_add3_u32 v11, v43, v11, s33
	v_bfe_u32 v43, v36, 16, 1
	v_bfe_u32 v56, v37, 16, 1
	v_bfe_u32 v57, v38, 16, 1
	v_bfe_u32 v58, v39, 16, 1
	v_add3_u32 v58, v39, v58, s33
	v_add3_u32 v57, v38, v57, s33
	v_add3_u32 v56, v37, v56, s33
	v_add3_u32 v43, v36, v43, s33
	v_lshrrev_b32_e32 v59, 16, v43
	v_lshrrev_b32_e32 v56, 16, v56
	v_lshrrev_b32_e32 v57, 16, v57
	v_lshrrev_b32_e32 v43, 16, v58
	v_and_or_b32 v43, v11, s29, v43
	v_and_or_b32 v42, v42, s29, v57
	v_and_or_b32 v41, v41, s29, v56
	v_and_or_b32 v40, v40, s29, v59
	s_waitcnt lgkmcnt(3)
	s_nop 1
	v_mfma_f32_16x16x32_bf16 v[36:39], v[116:119], v[40:43], v[44:47]
	s_waitcnt lgkmcnt(2)
	v_mfma_f32_16x16x32_bf16 v[44:47], v[120:123], v[40:43], v[52:55]
	s_waitcnt lgkmcnt(1)
	v_mfma_f32_16x16x32_bf16 v[52:55], v[124:127], v[40:43], v[62:65]
	s_waitcnt lgkmcnt(0)
	v_mfma_f32_16x16x32_bf16 v[40:43], v[128:131], v[40:43], v[48:51]
	ds_read2_b64 v[132:135], v3 offset0:32 offset1:36
	ds_read2_b64 v[136:139], v10 offset0:64 offset1:68
	ds_read2_b64 v[140:143], v60 offset0:96 offset1:100
	ds_read2_b64 v[144:147], v61 offset0:128 offset1:132
	v_mul_f32_e64 v32, v32, v2
	v_mul_f32_e64 v33, v33, v2
	v_pk_mul_f32 v[34:35], v[34:35], v[2:3] op_sel_hi:[1,0]
	v_pk_mul_f32 v[28:29], v[28:29], v[2:3] op_sel_hi:[1,0]
	v_pk_mul_f32 v[30:31], v[30:31], v[2:3] op_sel_hi:[1,0]
	v_bfe_u32 v11, v35, 16, 1
	v_bfe_u32 v48, v34, 16, 1
	v_bfe_u32 v49, v33, 16, 1
	v_bfe_u32 v50, v32, 16, 1
	v_add3_u32 v32, v32, v50, s33
	v_add3_u32 v33, v33, v49, s33
	v_add3_u32 v34, v34, v48, s33
	v_add3_u32 v11, v35, v11, s33
	v_bfe_u32 v35, v28, 16, 1
	v_bfe_u32 v48, v29, 16, 1
	v_bfe_u32 v49, v30, 16, 1
	v_bfe_u32 v50, v31, 16, 1
	v_add3_u32 v50, v31, v50, s33
	v_add3_u32 v49, v30, v49, s33
	v_add3_u32 v48, v29, v48, s33
	v_add3_u32 v35, v28, v35, s33
	v_lshrrev_b32_e32 v51, 16, v35
	v_lshrrev_b32_e32 v48, 16, v48
	v_lshrrev_b32_e32 v49, 16, v49
	v_lshrrev_b32_e32 v35, 16, v50
	v_and_or_b32 v35, v11, s29, v35
	v_and_or_b32 v34, v34, s29, v49
	v_and_or_b32 v33, v33, s29, v48
	v_and_or_b32 v32, v32, s29, v51
	s_waitcnt lgkmcnt(3)
	s_nop 1
	v_mfma_f32_16x16x32_bf16 v[28:31], v[132:135], v[32:35], v[36:39]
	s_waitcnt lgkmcnt(2)
	v_mfma_f32_16x16x32_bf16 v[36:39], v[136:139], v[32:35], v[44:47]
	s_waitcnt lgkmcnt(1)
	v_mfma_f32_16x16x32_bf16 v[44:47], v[140:143], v[32:35], v[52:55]
	s_waitcnt lgkmcnt(0)
	v_mfma_f32_16x16x32_bf16 v[32:35], v[144:147], v[32:35], v[40:43]
	ds_read2_b64 v[116:119], v3 offset0:40 offset1:44
	ds_read2_b64 v[120:123], v10 offset0:72 offset1:76
	ds_read2_b64 v[124:127], v60 offset0:104 offset1:108
	ds_read2_b64 v[128:131], v61 offset0:136 offset1:140
	v_mul_f32_e64 v24, v24, v2
	v_mul_f32_e64 v25, v25, v2
	v_pk_mul_f32 v[26:27], v[26:27], v[2:3] op_sel_hi:[1,0]
	v_pk_mul_f32 v[20:21], v[20:21], v[2:3] op_sel_hi:[1,0]
	v_pk_mul_f32 v[22:23], v[22:23], v[2:3] op_sel_hi:[1,0]
	v_bfe_u32 v11, v27, 16, 1
	v_bfe_u32 v40, v26, 16, 1
	v_bfe_u32 v41, v25, 16, 1
	v_bfe_u32 v42, v24, 16, 1
	v_add3_u32 v24, v24, v42, s33
	v_add3_u32 v25, v25, v41, s33
	v_add3_u32 v26, v26, v40, s33
	v_add3_u32 v11, v27, v11, s33
	v_bfe_u32 v27, v20, 16, 1
	v_bfe_u32 v40, v21, 16, 1
	v_bfe_u32 v41, v22, 16, 1
	v_bfe_u32 v42, v23, 16, 1
	v_add3_u32 v42, v23, v42, s33
	v_add3_u32 v41, v22, v41, s33
	v_add3_u32 v40, v21, v40, s33
	v_add3_u32 v27, v20, v27, s33
	v_lshrrev_b32_e32 v43, 16, v27
	v_lshrrev_b32_e32 v40, 16, v40
	v_lshrrev_b32_e32 v41, 16, v41
	v_lshrrev_b32_e32 v27, 16, v42
	v_and_or_b32 v27, v11, s29, v27
	v_and_or_b32 v26, v26, s29, v41
	v_and_or_b32 v25, v25, s29, v40
	v_and_or_b32 v24, v24, s29, v43
	s_waitcnt lgkmcnt(3)
	s_nop 1
	v_mfma_f32_16x16x32_bf16 v[20:23], v[116:119], v[24:27], v[28:31]
	s_waitcnt lgkmcnt(2)
	v_mfma_f32_16x16x32_bf16 v[28:31], v[120:123], v[24:27], v[36:39]
	s_waitcnt lgkmcnt(1)
	v_mfma_f32_16x16x32_bf16 v[36:39], v[124:127], v[24:27], v[44:47]
	s_waitcnt lgkmcnt(0)
	v_mfma_f32_16x16x32_bf16 v[24:27], v[128:131], v[24:27], v[32:35]
	ds_read2_b64 v[132:135], v3 offset0:48 offset1:52
	ds_read2_b64 v[136:139], v10 offset0:80 offset1:84
	ds_read2_b64 v[140:143], v60 offset0:112 offset1:116
	ds_read2_b64 v[144:147], v61 offset0:144 offset1:148
	v_mul_f32_e64 v16, v16, v2
	v_mul_f32_e64 v17, v17, v2
	v_pk_mul_f32 v[18:19], v[18:19], v[2:3] op_sel_hi:[1,0]
	v_pk_mul_f32 v[12:13], v[12:13], v[2:3] op_sel_hi:[1,0]
	v_pk_mul_f32 v[14:15], v[14:15], v[2:3] op_sel_hi:[1,0]
	v_bfe_u32 v11, v19, 16, 1
	v_bfe_u32 v32, v18, 16, 1
	v_bfe_u32 v33, v17, 16, 1
	v_bfe_u32 v34, v16, 16, 1
	v_add3_u32 v16, v16, v34, s33
	v_add3_u32 v17, v17, v33, s33
	v_add3_u32 v18, v18, v32, s33
	v_add3_u32 v11, v19, v11, s33
	v_bfe_u32 v19, v12, 16, 1
	v_bfe_u32 v32, v13, 16, 1
	v_bfe_u32 v33, v14, 16, 1
	v_bfe_u32 v34, v15, 16, 1
	v_add3_u32 v34, v15, v34, s33
	v_add3_u32 v33, v14, v33, s33
	v_add3_u32 v32, v13, v32, s33
	v_add3_u32 v19, v12, v19, s33
	v_lshrrev_b32_e32 v35, 16, v19
	v_lshrrev_b32_e32 v32, 16, v32
	v_lshrrev_b32_e32 v33, 16, v33
	v_lshrrev_b32_e32 v19, 16, v34
	v_and_or_b32 v19, v11, s29, v19
	v_and_or_b32 v18, v18, s29, v33
	v_and_or_b32 v17, v17, s29, v32
	v_and_or_b32 v16, v16, s29, v35
	s_waitcnt lgkmcnt(3)
	s_nop 1
	v_mfma_f32_16x16x32_bf16 v[12:15], v[132:135], v[16:19], v[20:23]
	s_waitcnt lgkmcnt(2)
	v_mfma_f32_16x16x32_bf16 v[20:23], v[136:139], v[16:19], v[28:31]
	s_waitcnt lgkmcnt(1)
	v_mfma_f32_16x16x32_bf16 v[28:31], v[140:143], v[16:19], v[36:39]
	s_waitcnt lgkmcnt(0)
	v_mfma_f32_16x16x32_bf16 v[16:19], v[144:147], v[16:19], v[24:27]
	ds_read2_b64 v[116:119], v3 offset0:56 offset1:60
	ds_read2_b64 v[120:123], v10 offset0:88 offset1:92
	ds_read2_b64 v[124:127], v60 offset0:120 offset1:124
	ds_read2_b64 v[128:131], v61 offset0:152 offset1:156
	v_mul_f32_e64 v8, v8, v2
	v_mul_f32_e64 v9, v9, v2
	v_pk_mul_f32 v[6:7], v[6:7], v[2:3] op_sel_hi:[1,0]
	v_pk_mul_f32 v[4:5], v[4:5], v[2:3] op_sel_hi:[1,0]
	v_pk_mul_f32 v[0:1], v[0:1], v[2:3] op_sel_hi:[1,0]
	v_bfe_u32 v2, v7, 16, 1
	v_bfe_u32 v24, v9, 16, 1
	v_bfe_u32 v25, v8, 16, 1
	v_add3_u32 v8, v8, v25, s33
	v_add3_u32 v9, v9, v24, s33
	v_add3_u32 v7, v7, v2, s33
	v_bfe_u32 v2, v4, 16, 1
	v_bfe_u32 v24, v0, 16, 1
	v_bfe_u32 v25, v1, 16, 1
	v_add3_u32 v25, v1, v25, s33
	v_add3_u32 v24, v0, v24, s33
	v_add3_u32 v4, v4, v2, s33
	v_bfe_u32 v11, v6, 16, 1
	v_add3_u32 v6, v6, v11, s33
	v_bfe_u32 v11, v5, 16, 1
	v_add3_u32 v5, v5, v11, s33
	v_lshrrev_b32_e32 v4, 16, v4
	v_lshrrev_b32_e32 v5, 16, v5
	v_lshrrev_b32_e32 v11, 16, v24
	v_lshrrev_b32_e32 v24, 16, v25
	v_and_or_b32 v27, v7, s29, v24
	v_and_or_b32 v26, v6, s29, v11
	v_and_or_b32 v25, v9, s29, v5
	v_and_or_b32 v24, v8, s29, v4
	s_waitcnt lgkmcnt(3)
	s_nop 1
	v_mfma_f32_16x16x32_bf16 v[12:15], v[116:119], v[24:27], v[12:15]
	s_waitcnt lgkmcnt(2)
	v_mfma_f32_16x16x32_bf16 v[8:11], v[120:123], v[24:27], v[20:23]
	s_waitcnt lgkmcnt(1)
	v_mfma_f32_16x16x32_bf16 v[4:7], v[124:127], v[24:27], v[28:31]
	s_waitcnt lgkmcnt(0)
	v_mfma_f32_16x16x32_bf16 v[0:3], v[128:131], v[24:27], v[16:19]
	s_and_b64 exec, exec, s[0:1]
	s_cbranch_execz .LBB0_153
	s_lshl_b32 s0, s17, 11
	v_bfe_u32 v18, v12, 16, 1
	s_add_u32 s0, s6, s0
	v_add3_u32 v12, v12, v18, s33
	v_bfe_u32 v18, v13, 16, 1
	s_addc_u32 s1, s7, 0
	v_add3_u32 v13, v13, v18, s33
	v_lshrrev_b32_e32 v12, 16, v12
	s_add_u32 s0, s0, s12
	v_and_or_b32 v12, v13, s29, v12
	v_bfe_u32 v13, v14, 16, 1
	s_addc_u32 s1, s1, 0
	v_lshlrev_b64 v[16:17], 11, v[68:69]
	v_add3_u32 v13, v14, v13, s33
	v_bfe_u32 v14, v15, 16, 1
	v_lshl_add_u64 v[16:17], s[0:1], 0, v[16:17]
	v_mov_b32_e32 v71, v80
	v_add3_u32 v14, v15, v14, s33
	v_lshrrev_b32_e32 v13, 16, v13
	v_lshl_add_u64 v[16:17], v[16:17], 0, v[70:71]
	v_and_or_b32 v13, v14, s29, v13
	global_store_dwordx2 v[16:17], v[12:13], off offset:1536
	v_bfe_u32 v12, v8, 16, 1
	v_add3_u32 v8, v8, v12, s33
	v_bfe_u32 v12, v9, 16, 1
	v_add3_u32 v9, v9, v12, s33
	v_lshrrev_b32_e32 v8, 16, v8
	v_and_or_b32 v8, v9, s29, v8
	v_bfe_u32 v9, v10, 16, 1
	v_add3_u32 v9, v10, v9, s33
	v_bfe_u32 v10, v11, 16, 1
	v_add3_u32 v10, v11, v10, s33
	v_lshrrev_b32_e32 v9, 16, v9
	v_and_or_b32 v9, v10, s29, v9
	global_store_dwordx2 v[16:17], v[8:9], off offset:1568
	v_bfe_u32 v8, v4, 16, 1
	v_add3_u32 v4, v4, v8, s33
	v_bfe_u32 v8, v5, 16, 1
	v_add3_u32 v5, v5, v8, s33
	v_lshrrev_b32_e32 v4, 16, v4
	v_and_or_b32 v4, v5, s29, v4
	v_bfe_u32 v5, v6, 16, 1
	v_add3_u32 v5, v6, v5, s33
	v_bfe_u32 v6, v7, 16, 1
	v_add3_u32 v6, v7, v6, s33
	v_lshrrev_b32_e32 v5, 16, v5
	v_and_or_b32 v5, v6, s29, v5
	global_store_dwordx2 v[16:17], v[4:5], off offset:1600
	v_bfe_u32 v4, v0, 16, 1
	v_add3_u32 v0, v0, v4, s33
	v_bfe_u32 v4, v1, 16, 1
	v_add3_u32 v1, v1, v4, s33
	v_lshrrev_b32_e32 v0, 16, v0
	v_and_or_b32 v0, v1, s29, v0
	v_bfe_u32 v1, v2, 16, 1
	v_add3_u32 v1, v2, v1, s33
	v_bfe_u32 v2, v3, 16, 1
	v_add3_u32 v2, v3, v2, s33
	v_lshrrev_b32_e32 v1, 16, v1
	v_and_or_b32 v1, v2, s29, v1
	global_store_dwordx2 v[16:17], v[0:1], off offset:1632

.LBB0_256:
	ds_read_b128 v[12:15], v82
	ds_read_b128 v[16:19], v82 offset:64
	s_waitcnt lgkmcnt(1)
	v_mfma_f32_16x16x32_bf16 v[12:15], v[12:15], v[72:75], 0
	ds_read_b128 v[86:89], v82 offset:32320
	s_waitcnt lgkmcnt(1)
	v_mfma_f32_16x16x32_bf16 v[68:71], v[16:19], v[8:11], v[12:15]
	ds_read_b128 v[16:19], v82 offset:2368
	s_nop 3
	ds_read_b128 v[12:15], v82 offset:2304
	s_waitcnt lgkmcnt(0)
	v_mfma_f32_16x16x32_bf16 v[12:15], v[12:15], v[72:75], 0
	v_mfma_f32_16x16x32_bf16 v[64:67], v[16:19], v[8:11], v[12:15]
	ds_read_b128 v[16:19], v82 offset:4672
	s_nop 5
	ds_read_b128 v[12:15], v82 offset:4608
	s_waitcnt lgkmcnt(0)
	v_mfma_f32_16x16x32_bf16 v[12:15], v[12:15], v[72:75], 0
	v_mfma_f32_16x16x32_bf16 v[60:63], v[16:19], v[8:11], v[12:15]
	ds_read_b128 v[16:19], v82 offset:6976
	s_nop 5
	ds_read_b128 v[12:15], v82 offset:6912
	s_waitcnt lgkmcnt(0)
	v_mfma_f32_16x16x32_bf16 v[12:15], v[12:15], v[72:75], 0
	v_mfma_f32_16x16x32_bf16 v[56:59], v[16:19], v[8:11], v[12:15]
	ds_read_b128 v[16:19], v82 offset:9280
	s_nop 5
	ds_read_b128 v[12:15], v82 offset:9216
	s_waitcnt lgkmcnt(0)
	v_mfma_f32_16x16x32_bf16 v[12:15], v[12:15], v[72:75], 0
	v_mfma_f32_16x16x32_bf16 v[52:55], v[16:19], v[8:11], v[12:15]
	ds_read_b128 v[16:19], v82 offset:11584
	s_nop 5
	ds_read_b128 v[12:15], v82 offset:11520
	s_waitcnt lgkmcnt(0)
	v_mfma_f32_16x16x32_bf16 v[12:15], v[12:15], v[72:75], 0
	v_mfma_f32_16x16x32_bf16 v[48:51], v[16:19], v[8:11], v[12:15]
	ds_read_b128 v[16:19], v82 offset:13888
	s_nop 5
	ds_read_b128 v[12:15], v82 offset:13824
	s_waitcnt lgkmcnt(0)
	v_mfma_f32_16x16x32_bf16 v[12:15], v[12:15], v[72:75], 0
	v_mfma_f32_16x16x32_bf16 v[44:47], v[16:19], v[8:11], v[12:15]
	ds_read_b128 v[16:19], v82 offset:16192
	s_nop 5
	ds_read_b128 v[12:15], v82 offset:16128
	s_waitcnt lgkmcnt(0)
	v_mfma_f32_16x16x32_bf16 v[12:15], v[12:15], v[72:75], 0
	v_mfma_f32_16x16x32_bf16 v[40:43], v[16:19], v[8:11], v[12:15]
	ds_read_b128 v[16:19], v82 offset:18496
	s_nop 5
	ds_read_b128 v[12:15], v82 offset:18432
	s_waitcnt lgkmcnt(0)
	v_mfma_f32_16x16x32_bf16 v[12:15], v[12:15], v[72:75], 0
	v_mfma_f32_16x16x32_bf16 v[36:39], v[16:19], v[8:11], v[12:15]
	ds_read_b128 v[16:19], v82 offset:20800
	s_nop 5
	ds_read_b128 v[12:15], v82 offset:20736
	s_waitcnt lgkmcnt(0)
	v_mfma_f32_16x16x32_bf16 v[12:15], v[12:15], v[72:75], 0
	v_mfma_f32_16x16x32_bf16 v[32:35], v[16:19], v[8:11], v[12:15]
	ds_read_b128 v[16:19], v82 offset:23104
	s_nop 5
	ds_read_b128 v[12:15], v82 offset:23040
	s_waitcnt lgkmcnt(0)
	v_mfma_f32_16x16x32_bf16 v[12:15], v[12:15], v[72:75], 0
	v_mfma_f32_16x16x32_bf16 v[28:31], v[16:19], v[8:11], v[12:15]
	ds_read_b128 v[16:19], v82 offset:25408
	s_nop 5
	ds_read_b128 v[12:15], v82 offset:25344
	s_waitcnt lgkmcnt(0)
	v_mfma_f32_16x16x32_bf16 v[12:15], v[12:15], v[72:75], 0
	v_mfma_f32_16x16x32_bf16 v[24:27], v[16:19], v[8:11], v[12:15]
	ds_read_b128 v[16:19], v82 offset:27712
	s_nop 5
	ds_read_b128 v[12:15], v82 offset:27648
	s_waitcnt lgkmcnt(0)
	v_mfma_f32_16x16x32_bf16 v[12:15], v[12:15], v[72:75], 0
	v_mfma_f32_16x16x32_bf16 v[20:23], v[16:19], v[8:11], v[12:15]
	ds_read_b128 v[16:19], v82 offset:30016
	s_nop 5
	ds_read_b128 v[12:15], v82 offset:29952
	s_waitcnt lgkmcnt(0)
	v_mfma_f32_16x16x32_bf16 v[12:15], v[12:15], v[72:75], 0
	v_mfma_f32_16x16x32_bf16 v[16:19], v[16:19], v[8:11], v[12:15]
	s_nop 6
	ds_read_b128 v[12:15], v82 offset:32256
	s_waitcnt lgkmcnt(0)
	v_mfma_f32_16x16x32_bf16 v[12:15], v[12:15], v[72:75], 0
	v_mfma_f32_16x16x32_bf16 v[12:15], v[86:89], v[8:11], v[12:15]
	ds_read_b128 v[86:89], v82 offset:34560
	s_waitcnt lgkmcnt(0)
	v_mfma_f32_16x16x32_bf16 v[72:75], v[86:89], v[72:75], 0
	ds_read_b128 v[86:89], v82 offset:34624
	s_waitcnt lgkmcnt(0)
	v_mfma_f32_16x16x32_bf16 v[8:11], v[86:89], v[8:11], v[72:75]
	s_nop 4
	v_mul_f32_e32 v72, 0x3e000000, v68
	v_mul_f32_e32 v73, 0x3e000000, v69
	s_mov_b32 s2, 0xff61b1e6
	v_max3_f32 v72, v72, s2, v73
	v_mul_f32_e32 v73, 0x3e000000, v70
	v_mul_f32_e32 v74, 0x3e000000, v71
	v_max3_f32 v72, v72, v73, v74
	v_mul_f32_e32 v73, 0x3e000000, v64
	v_mul_f32_e32 v74, 0x3e000000, v65
	v_max3_f32 v72, v72, v73, v74
	v_mul_f32_e32 v73, 0x3e000000, v66
	v_mul_f32_e32 v74, 0x3e000000, v67
	v_max3_f32 v72, v72, v73, v74
	v_mul_f32_e32 v73, 0x3e000000, v60
	v_mul_f32_e32 v74, 0x3e000000, v61
	v_max3_f32 v72, v72, v73, v74
	v_mul_f32_e32 v73, 0x3e000000, v62
	v_mul_f32_e32 v74, 0x3e000000, v63
	v_max3_f32 v72, v72, v73, v74
	v_mul_f32_e32 v73, 0x3e000000, v56
	v_mul_f32_e32 v74, 0x3e000000, v57
	v_max3_f32 v72, v72, v73, v74
	v_mul_f32_e32 v73, 0x3e000000, v58
	v_mul_f32_e32 v74, 0x3e000000, v59
	v_max3_f32 v72, v72, v73, v74
	v_mul_f32_e32 v73, 0x3e000000, v52
	v_mul_f32_e32 v74, 0x3e000000, v53
	v_max3_f32 v72, v72, v73, v74
	v_mul_f32_e32 v73, 0x3e000000, v54
	v_mul_f32_e32 v74, 0x3e000000, v55
	v_max3_f32 v72, v72, v73, v74
	v_mul_f32_e32 v73, 0x3e000000, v48
	v_mul_f32_e32 v74, 0x3e000000, v49
	v_max3_f32 v72, v72, v73, v74
	v_mul_f32_e32 v73, 0x3e000000, v50
	v_mul_f32_e32 v74, 0x3e000000, v51
	v_max3_f32 v72, v72, v73, v74
	v_mul_f32_e32 v73, 0x3e000000, v44
	v_mul_f32_e32 v74, 0x3e000000, v45
	v_max3_f32 v72, v72, v73, v74
	v_mul_f32_e32 v73, 0x3e000000, v46
	v_mul_f32_e32 v74, 0x3e000000, v47
	v_max3_f32 v72, v72, v73, v74
	v_mul_f32_e32 v73, 0x3e000000, v40
	v_mul_f32_e32 v74, 0x3e000000, v41
	v_max3_f32 v72, v72, v73, v74
	v_mul_f32_e32 v73, 0x3e000000, v42
	v_mul_f32_e32 v74, 0x3e000000, v43
	v_max3_f32 v72, v72, v73, v74
	v_mul_f32_e32 v73, 0x3e000000, v36
	v_mul_f32_e32 v74, 0x3e000000, v37
	v_max3_f32 v72, v72, v73, v74
	v_mul_f32_e32 v73, 0x3e000000, v38
	v_mul_f32_e32 v74, 0x3e000000, v39
	v_max3_f32 v72, v72, v73, v74
	v_mul_f32_e32 v73, 0x3e000000, v32
	v_mul_f32_e32 v74, 0x3e000000, v33
	v_max3_f32 v72, v72, v73, v74
	v_mul_f32_e32 v73, 0x3e000000, v34
	v_mul_f32_e32 v74, 0x3e000000, v35
	v_max3_f32 v72, v72, v73, v74
	v_mul_f32_e32 v73, 0x3e000000, v28
	v_mul_f32_e32 v74, 0x3e000000, v29
	v_max3_f32 v72, v72, v73, v74
	v_mul_f32_e32 v73, 0x3e000000, v30
	v_mul_f32_e32 v74, 0x3e000000, v31
	v_max3_f32 v72, v72, v73, v74
	v_mul_f32_e32 v73, 0x3e000000, v24
	v_mul_f32_e32 v74, 0x3e000000, v25
	v_max3_f32 v72, v72, v73, v74
	v_mul_f32_e32 v73, 0x3e000000, v26
	v_mul_f32_e32 v74, 0x3e000000, v27
	v_max3_f32 v72, v72, v73, v74
	v_mul_f32_e32 v73, 0x3e000000, v20
	v_mul_f32_e32 v74, 0x3e000000, v21
	v_max3_f32 v72, v72, v73, v74
	v_mul_f32_e32 v73, 0x3e000000, v22
	v_mul_f32_e32 v74, 0x3e000000, v23
	v_max3_f32 v72, v72, v73, v74
	v_mul_f32_e32 v73, 0x3e000000, v16
	v_mul_f32_e32 v74, 0x3e000000, v17
	v_max3_f32 v72, v72, v73, v74
	v_mul_f32_e32 v73, 0x3e000000, v18
	v_mul_f32_e32 v74, 0x3e000000, v19
	v_max3_f32 v72, v72, v73, v74
	v_mul_f32_e32 v73, 0x3e000000, v12
	v_mul_f32_e32 v74, 0x3e000000, v13
	v_max3_f32 v72, v72, v73, v74
	v_mul_f32_e32 v73, 0x3e000000, v14
	v_mul_f32_e32 v74, 0x3e000000, v15
	v_max3_f32 v72, v72, v73, v74
	v_mul_f32_e32 v73, 0x3e000000, v8
	v_mul_f32_e32 v74, 0x3e000000, v9
	v_max3_f32 v72, v72, v73, v74
	v_mul_f32_e32 v73, 0x3e000000, v10
	v_mul_f32_e32 v74, 0x3e000000, v11
	v_max3_f32 v72, v72, v73, v74
	ds_bpermute_b32 v73, v83, v72
	s_mov_b32 s2, 0x3e000000
	s_waitcnt lgkmcnt(0)
	v_max_f32_e32 v73, v73, v73
	v_max_f32_e32 v72, v72, v73
	ds_bpermute_b32 v73, v84, v72
	s_waitcnt lgkmcnt(0)
	v_max_f32_e32 v73, v73, v73
	v_max_f32_e32 v86, v72, v73
	v_fma_f32 v68, v68, s2, -v86
	v_fma_f32 v69, v69, s2, -v86
	v_mul_f32_e32 v68, 0x3fb8aa3b, v68
	v_mul_f32_e32 v69, 0x3fb8aa3b, v69
	v_exp_f32_e32 v68, v68
	v_exp_f32_e32 v72, v69
	v_fma_f32 v69, v70, s2, -v86
	v_mul_f32_e32 v69, 0x3fb8aa3b, v69
	v_fma_f32 v70, v71, s2, -v86
	v_exp_f32_e32 v69, v69
	v_mul_f32_e32 v70, 0x3fb8aa3b, v70
	v_exp_f32_e32 v73, v70
	v_add_f32_e32 v70, 0, v68
	v_add_f32_e32 v70, v72, v70
	v_fma_f32 v64, v64, s2, -v86
	v_add_f32_e32 v70, v69, v70
	v_mul_f32_e32 v64, 0x3fb8aa3b, v64
	v_add_f32_e32 v87, v73, v70
	v_exp_f32_e32 v70, v64
	v_fma_f32 v64, v65, s2, -v86
	v_mul_f32_e32 v64, 0x3fb8aa3b, v64
	v_exp_f32_e32 v74, v64
	v_fma_f32 v64, v66, s2, -v86
	v_mul_f32_e32 v64, 0x3fb8aa3b, v64
	v_exp_f32_e32 v71, v64
	v_fma_f32 v64, v67, s2, -v86
	v_mul_f32_e32 v64, 0x3fb8aa3b, v64
	v_exp_f32_e32 v75, v64
	v_add_f32_e32 v64, v70, v87
	v_add_f32_e32 v64, v74, v64
	v_fma_f32 v60, v60, s2, -v86
	v_fma_f32 v61, v61, s2, -v86
	v_add_f32_e32 v64, v71, v64
	v_mul_f32_e32 v60, 0x3fb8aa3b, v60
	v_mul_f32_e32 v61, 0x3fb8aa3b, v61
	v_add_f32_e32 v66, v75, v64
	v_exp_f32_e32 v60, v60
	v_exp_f32_e32 v64, v61
	v_fma_f32 v61, v62, s2, -v86
	v_mul_f32_e32 v61, 0x3fb8aa3b, v61
	v_fma_f32 v62, v63, s2, -v86
	v_exp_f32_e32 v61, v61
	v_mul_f32_e32 v62, 0x3fb8aa3b, v62
	v_exp_f32_e32 v65, v62
	v_add_f32_e32 v62, v60, v66
	v_add_f32_e32 v62, v64, v62
	v_fma_f32 v56, v56, s2, -v86
	v_add_f32_e32 v62, v61, v62
	v_mul_f32_e32 v56, 0x3fb8aa3b, v56
	v_add_f32_e32 v87, v65, v62
	v_exp_f32_e32 v62, v56
	v_fma_f32 v56, v57, s2, -v86
	v_mul_f32_e32 v56, 0x3fb8aa3b, v56
	v_exp_f32_e32 v66, v56
	v_fma_f32 v56, v58, s2, -v86
	v_mul_f32_e32 v56, 0x3fb8aa3b, v56
	v_exp_f32_e32 v63, v56
	v_fma_f32 v56, v59, s2, -v86
	v_mul_f32_e32 v56, 0x3fb8aa3b, v56
	v_exp_f32_e32 v67, v56
	v_add_f32_e32 v56, v62, v87
	v_add_f32_e32 v56, v66, v56
	v_fma_f32 v52, v52, s2, -v86
	v_fma_f32 v53, v53, s2, -v86
	v_add_f32_e32 v56, v63, v56
	v_mul_f32_e32 v52, 0x3fb8aa3b, v52
	v_mul_f32_e32 v53, 0x3fb8aa3b, v53
	v_add_f32_e32 v58, v67, v56
	v_exp_f32_e32 v52, v52
	v_exp_f32_e32 v56, v53
	v_fma_f32 v53, v54, s2, -v86
	v_mul_f32_e32 v53, 0x3fb8aa3b, v53
	v_fma_f32 v54, v55, s2, -v86
	v_exp_f32_e32 v53, v53
	v_mul_f32_e32 v54, 0x3fb8aa3b, v54
	v_exp_f32_e32 v57, v54
	v_add_f32_e32 v54, v52, v58
	v_add_f32_e32 v54, v56, v54
	v_fma_f32 v48, v48, s2, -v86
	v_add_f32_e32 v54, v53, v54
	v_mul_f32_e32 v48, 0x3fb8aa3b, v48
	v_add_f32_e32 v87, v57, v54
	v_exp_f32_e32 v54, v48
	v_fma_f32 v48, v49, s2, -v86
	v_mul_f32_e32 v48, 0x3fb8aa3b, v48
	v_exp_f32_e32 v58, v48
	v_fma_f32 v48, v50, s2, -v86
	v_mul_f32_e32 v48, 0x3fb8aa3b, v48
	v_exp_f32_e32 v55, v48
	v_fma_f32 v48, v51, s2, -v86
	v_mul_f32_e32 v48, 0x3fb8aa3b, v48
	v_exp_f32_e32 v59, v48
	v_add_f32_e32 v48, v54, v87
	v_add_f32_e32 v48, v58, v48
	v_fma_f32 v44, v44, s2, -v86
	v_fma_f32 v45, v45, s2, -v86
	v_add_f32_e32 v48, v55, v48
	v_mul_f32_e32 v44, 0x3fb8aa3b, v44
	v_mul_f32_e32 v45, 0x3fb8aa3b, v45
	v_add_f32_e32 v50, v59, v48
	v_exp_f32_e32 v44, v44
	v_exp_f32_e32 v48, v45
	v_fma_f32 v45, v46, s2, -v86
	v_mul_f32_e32 v45, 0x3fb8aa3b, v45
	v_fma_f32 v46, v47, s2, -v86
	v_exp_f32_e32 v45, v45
	v_mul_f32_e32 v46, 0x3fb8aa3b, v46
	v_exp_f32_e32 v49, v46
	v_add_f32_e32 v46, v44, v50
	v_add_f32_e32 v46, v48, v46
	v_fma_f32 v40, v40, s2, -v86
	v_add_f32_e32 v46, v45, v46
	v_mul_f32_e32 v40, 0x3fb8aa3b, v40
	v_add_f32_e32 v87, v49, v46
	v_exp_f32_e32 v46, v40
	v_fma_f32 v40, v41, s2, -v86
	v_mul_f32_e32 v40, 0x3fb8aa3b, v40
	v_exp_f32_e32 v50, v40
	v_fma_f32 v40, v42, s2, -v86
	v_mul_f32_e32 v40, 0x3fb8aa3b, v40
	v_exp_f32_e32 v47, v40
	v_fma_f32 v40, v43, s2, -v86
	v_mul_f32_e32 v40, 0x3fb8aa3b, v40
	v_exp_f32_e32 v51, v40
	v_add_f32_e32 v40, v46, v87
	v_add_f32_e32 v40, v50, v40
	v_fma_f32 v36, v36, s2, -v86
	v_fma_f32 v37, v37, s2, -v86
	v_add_f32_e32 v40, v47, v40
	v_mul_f32_e32 v36, 0x3fb8aa3b, v36
	v_mul_f32_e32 v37, 0x3fb8aa3b, v37
	v_add_f32_e32 v42, v51, v40
	v_exp_f32_e32 v36, v36
	v_exp_f32_e32 v40, v37
	v_fma_f32 v37, v38, s2, -v86
	v_mul_f32_e32 v37, 0x3fb8aa3b, v37
	v_fma_f32 v38, v39, s2, -v86
	v_exp_f32_e32 v37, v37
	v_mul_f32_e32 v38, 0x3fb8aa3b, v38
	v_exp_f32_e32 v41, v38
	v_add_f32_e32 v38, v36, v42
	v_add_f32_e32 v38, v40, v38
	v_fma_f32 v32, v32, s2, -v86
	v_add_f32_e32 v38, v37, v38
	v_mul_f32_e32 v32, 0x3fb8aa3b, v32
	v_add_f32_e32 v87, v41, v38
	v_exp_f32_e32 v38, v32
	v_fma_f32 v32, v33, s2, -v86
	v_mul_f32_e32 v32, 0x3fb8aa3b, v32
	v_exp_f32_e32 v42, v32
	v_fma_f32 v32, v34, s2, -v86
	v_mul_f32_e32 v32, 0x3fb8aa3b, v32
	v_exp_f32_e32 v39, v32
	v_fma_f32 v32, v35, s2, -v86
	v_mul_f32_e32 v32, 0x3fb8aa3b, v32
	v_exp_f32_e32 v43, v32
	v_add_f32_e32 v32, v38, v87
	v_add_f32_e32 v32, v42, v32
	v_fma_f32 v28, v28, s2, -v86
	v_fma_f32 v29, v29, s2, -v86
	v_add_f32_e32 v32, v39, v32
	v_mul_f32_e32 v28, 0x3fb8aa3b, v28
	v_mul_f32_e32 v29, 0x3fb8aa3b, v29
	v_add_f32_e32 v34, v43, v32
	v_exp_f32_e32 v28, v28
	v_exp_f32_e32 v32, v29
	v_fma_f32 v29, v30, s2, -v86
	v_mul_f32_e32 v29, 0x3fb8aa3b, v29
	v_fma_f32 v30, v31, s2, -v86
	v_exp_f32_e32 v29, v29
	v_mul_f32_e32 v30, 0x3fb8aa3b, v30
	v_exp_f32_e32 v33, v30
	v_add_f32_e32 v30, v28, v34
	v_add_f32_e32 v30, v32, v30
	v_fma_f32 v24, v24, s2, -v86
	v_add_f32_e32 v30, v29, v30
	v_mul_f32_e32 v24, 0x3fb8aa3b, v24
	v_add_f32_e32 v87, v33, v30
	v_exp_f32_e32 v30, v24
	v_fma_f32 v24, v25, s2, -v86
	v_mul_f32_e32 v24, 0x3fb8aa3b, v24
	v_exp_f32_e32 v34, v24
	v_fma_f32 v24, v26, s2, -v86
	v_mul_f32_e32 v24, 0x3fb8aa3b, v24
	v_exp_f32_e32 v31, v24
	v_fma_f32 v24, v27, s2, -v86
	v_mul_f32_e32 v24, 0x3fb8aa3b, v24
	v_exp_f32_e32 v35, v24
	v_add_f32_e32 v24, v30, v87
	v_add_f32_e32 v24, v34, v24
	v_fma_f32 v20, v20, s2, -v86
	v_fma_f32 v21, v21, s2, -v86
	v_add_f32_e32 v24, v31, v24
	v_mul_f32_e32 v20, 0x3fb8aa3b, v20
	v_mul_f32_e32 v21, 0x3fb8aa3b, v21
	v_add_f32_e32 v26, v35, v24
	v_exp_f32_e32 v20, v20
	v_exp_f32_e32 v24, v21
	v_fma_f32 v21, v22, s2, -v86
	v_mul_f32_e32 v21, 0x3fb8aa3b, v21
	v_fma_f32 v22, v23, s2, -v86
	v_exp_f32_e32 v21, v21
	v_mul_f32_e32 v22, 0x3fb8aa3b, v22
	v_exp_f32_e32 v25, v22
	v_add_f32_e32 v22, v20, v26
	v_add_f32_e32 v22, v24, v22
	v_fma_f32 v16, v16, s2, -v86
	v_add_f32_e32 v22, v21, v22
	v_mul_f32_e32 v16, 0x3fb8aa3b, v16
	v_add_f32_e32 v87, v25, v22
	v_exp_f32_e32 v22, v16
	v_fma_f32 v16, v17, s2, -v86
	v_mul_f32_e32 v16, 0x3fb8aa3b, v16
	v_exp_f32_e32 v26, v16
	v_fma_f32 v16, v18, s2, -v86
	v_mul_f32_e32 v16, 0x3fb8aa3b, v16
	v_exp_f32_e32 v23, v16
	v_fma_f32 v16, v19, s2, -v86
	v_mul_f32_e32 v16, 0x3fb8aa3b, v16
	v_exp_f32_e32 v27, v16
	v_add_f32_e32 v16, v22, v87
	v_add_f32_e32 v16, v26, v16
	v_fma_f32 v12, v12, s2, -v86
	v_fma_f32 v13, v13, s2, -v86
	v_add_f32_e32 v16, v23, v16
	v_mul_f32_e32 v12, 0x3fb8aa3b, v12
	v_mul_f32_e32 v13, 0x3fb8aa3b, v13
	v_add_f32_e32 v18, v27, v16
	v_exp_f32_e32 v12, v12
	v_exp_f32_e32 v16, v13
	v_fma_f32 v13, v14, s2, -v86
	v_mul_f32_e32 v13, 0x3fb8aa3b, v13
	v_fma_f32 v14, v15, s2, -v86
	v_exp_f32_e32 v13, v13
	v_mul_f32_e32 v14, 0x3fb8aa3b, v14
	v_exp_f32_e32 v17, v14
	v_add_f32_e32 v14, v12, v18
	v_add_f32_e32 v14, v16, v14
	v_fma_f32 v8, v8, s2, -v86
	v_fma_f32 v9, v9, s2, -v86
	v_add_f32_e32 v14, v13, v14
	v_mul_f32_e32 v8, 0x3fb8aa3b, v8
	v_mul_f32_e32 v9, 0x3fb8aa3b, v9
	v_add_f32_e32 v18, v17, v14
	v_exp_f32_e32 v8, v8
	v_exp_f32_e32 v14, v9
	v_fma_f32 v9, v10, s2, -v86
	v_mul_f32_e32 v9, 0x3fb8aa3b, v9
	v_fma_f32 v10, v11, s2, -v86
	v_exp_f32_e32 v9, v9
	v_mul_f32_e32 v10, 0x3fb8aa3b, v10
	v_exp_f32_e32 v15, v10
	v_add_f32_e32 v10, v8, v18
	v_add_f32_e32 v10, v14, v10
	v_add_f32_e32 v10, v9, v10
	v_add_f32_e32 v10, v15, v10
	ds_bpermute_b32 v11, v83, v10
	s_waitcnt lgkmcnt(0)
	v_add_f32_e32 v10, v10, v11
	ds_bpermute_b32 v11, v84, v10
	s_waitcnt lgkmcnt(0)
	v_add_f32_e32 v10, v10, v11
	v_div_scale_f32 v11, s[2:3], v10, v10, 1.0
	v_rcp_f32_e32 v18, v11
	v_div_scale_f32 v19, vcc, 1.0, v10, 1.0
	v_fma_f32 v86, -v11, v18, 1.0
	v_fmac_f32_e32 v18, v86, v18
	v_mul_f32_e32 v86, v19, v18
	v_fma_f32 v87, -v11, v86, v19
	v_fmac_f32_e32 v86, v87, v18
	v_fma_f32 v11, -v11, v86, v19
	v_div_fmas_f32 v11, v11, v18, v86
	v_div_fixup_f32 v10, v11, v10, 1.0
	v_pk_mul_f32 v[18:19], v[68:69], v[10:11] op_sel_hi:[1,0]
	v_pk_mul_f32 v[68:69], v[72:73], v[10:11] op_sel_hi:[1,0]
	v_pk_mul_f32 v[72:73], v[74:75], v[10:11] op_sel_hi:[1,0]
	v_pk_mul_f32 v[70:71], v[70:71], v[10:11] op_sel_hi:[1,0]
	v_bfe_u32 v11, v73, 16, 1
	v_bfe_u32 v74, v72, 16, 1
	v_bfe_u32 v75, v69, 16, 1
	v_bfe_u32 v86, v68, 16, 1
	v_add3_u32 v73, v73, v11, s33
	v_bfe_u32 v11, v18, 16, 1
	v_add3_u32 v86, v68, v86, s33
	v_add3_u32 v87, v69, v75, s33
	v_add3_u32 v72, v72, v74, s33
	v_bfe_u32 v68, v19, 16, 1
	v_bfe_u32 v69, v70, 16, 1
	v_bfe_u32 v74, v71, 16, 1
	v_add3_u32 v18, v18, v11, s33
	v_add_u32_e32 v11, 0x9000, v85
	v_add3_u32 v74, v71, v74, s33
	v_add3_u32 v75, v70, v69, s33
	v_add3_u32 v19, v19, v68, s33
	ds_read2_b64 v[68:71], v11 offset1:4
	v_lshrrev_b32_e32 v18, 16, v18
	v_lshrrev_b32_e32 v19, 16, v19
	v_lshrrev_b32_e32 v88, 16, v75
	v_lshrrev_b32_e32 v74, 16, v74
	v_and_or_b32 v75, v73, s29, v74
	v_and_or_b32 v74, v72, s29, v88
	v_and_or_b32 v73, v87, s29, v19
	v_and_or_b32 v72, v86, s29, v18
	v_add_u32_e32 v18, 0xb000, v85
	s_waitcnt lgkmcnt(0)
	v_mfma_f32_16x16x32_bf16 v[86:89], v[68:71], v[72:75], 0
	ds_read2_b64 v[68:71], v18 offset0:32 offset1:36
	s_waitcnt lgkmcnt(0)
	v_mfma_f32_16x16x32_bf16 v[90:93], v[68:71], v[72:75], 0
	v_add_u32_e32 v68, 0xd000, v85
	v_add_u32_e32 v69, 0xf000, v85
	ds_read2_b64 v[94:97], v68 offset0:64 offset1:68
	ds_read2_b64 v[98:101], v69 offset0:96 offset1:100
	s_waitcnt lgkmcnt(1)
	v_mfma_f32_16x16x32_bf16 v[94:97], v[94:97], v[72:75], 0
	s_waitcnt lgkmcnt(0)
	v_mfma_f32_16x16x32_bf16 v[70:73], v[98:101], v[72:75], 0
	ds_read2_b64 v[132:135], v11 offset0:8 offset1:12
	ds_read2_b64 v[136:139], v18 offset0:40 offset1:44
	ds_read2_b64 v[140:143], v68 offset0:72 offset1:76
	ds_read2_b64 v[144:147], v69 offset0:104 offset1:108
	v_mul_f32_e64 v64, v64, v10
	v_mul_f32_e64 v65, v65, v10
	v_pk_mul_f32 v[66:67], v[66:67], v[10:11] op_sel_hi:[1,0]
	v_pk_mul_f32 v[60:61], v[60:61], v[10:11] op_sel_hi:[1,0]
	v_pk_mul_f32 v[62:63], v[62:63], v[10:11] op_sel_hi:[1,0]
	v_bfe_u32 v19, v67, 16, 1
	v_bfe_u32 v74, v66, 16, 1
	v_bfe_u32 v75, v65, 16, 1
	v_bfe_u32 v98, v64, 16, 1
	v_add3_u32 v64, v64, v98, s33
	v_add3_u32 v65, v65, v75, s33
	v_add3_u32 v66, v66, v74, s33
	v_add3_u32 v19, v67, v19, s33
	v_bfe_u32 v67, v60, 16, 1
	v_bfe_u32 v74, v61, 16, 1
	v_bfe_u32 v75, v62, 16, 1
	v_bfe_u32 v98, v63, 16, 1
	v_add3_u32 v98, v63, v98, s33
	v_add3_u32 v75, v62, v75, s33
	v_add3_u32 v74, v61, v74, s33
	v_add3_u32 v67, v60, v67, s33
	v_lshrrev_b32_e32 v99, 16, v67
	v_lshrrev_b32_e32 v74, 16, v74
	v_lshrrev_b32_e32 v75, 16, v75
	v_lshrrev_b32_e32 v67, 16, v98
	v_and_or_b32 v67, v19, s29, v67
	v_and_or_b32 v66, v66, s29, v75
	v_and_or_b32 v65, v65, s29, v74
	v_and_or_b32 v64, v64, s29, v99
	s_waitcnt lgkmcnt(3)
	s_nop 1
	v_mfma_f32_16x16x32_bf16 v[60:63], v[132:135], v[64:67], v[86:89]
	s_waitcnt lgkmcnt(2)
	v_mfma_f32_16x16x32_bf16 v[86:89], v[136:139], v[64:67], v[90:93]
	s_waitcnt lgkmcnt(1)
	v_mfma_f32_16x16x32_bf16 v[90:93], v[140:143], v[64:67], v[94:97]
	s_waitcnt lgkmcnt(0)
	v_mfma_f32_16x16x32_bf16 v[64:67], v[144:147], v[64:67], v[70:73]
	ds_read2_b64 v[116:119], v11 offset0:16 offset1:20
	ds_read2_b64 v[120:123], v18 offset0:48 offset1:52
	ds_read2_b64 v[124:127], v68 offset0:80 offset1:84
	ds_read2_b64 v[128:131], v69 offset0:112 offset1:116
	v_mul_f32_e64 v56, v56, v10
	v_mul_f32_e64 v57, v57, v10
	v_pk_mul_f32 v[58:59], v[58:59], v[10:11] op_sel_hi:[1,0]
	v_pk_mul_f32 v[52:53], v[52:53], v[10:11] op_sel_hi:[1,0]
	v_pk_mul_f32 v[54:55], v[54:55], v[10:11] op_sel_hi:[1,0]
	v_bfe_u32 v19, v59, 16, 1
	v_bfe_u32 v70, v58, 16, 1
	v_bfe_u32 v71, v57, 16, 1
	v_bfe_u32 v72, v56, 16, 1
	v_add3_u32 v56, v56, v72, s33
	v_add3_u32 v57, v57, v71, s33
	v_add3_u32 v58, v58, v70, s33
	v_add3_u32 v19, v59, v19, s33
	v_bfe_u32 v59, v52, 16, 1
	v_bfe_u32 v70, v53, 16, 1
	v_bfe_u32 v71, v54, 16, 1
	v_bfe_u32 v72, v55, 16, 1
	v_add3_u32 v72, v55, v72, s33
	v_add3_u32 v71, v54, v71, s33
	v_add3_u32 v70, v53, v70, s33
	v_add3_u32 v59, v52, v59, s33
	v_lshrrev_b32_e32 v73, 16, v59
	v_lshrrev_b32_e32 v70, 16, v70
	v_lshrrev_b32_e32 v71, 16, v71
	v_lshrrev_b32_e32 v59, 16, v72
	v_and_or_b32 v59, v19, s29, v59
	v_and_or_b32 v58, v58, s29, v71
	v_and_or_b32 v57, v57, s29, v70
	v_and_or_b32 v56, v56, s29, v73
	s_waitcnt lgkmcnt(3)
	s_nop 1
	v_mfma_f32_16x16x32_bf16 v[52:55], v[116:119], v[56:59], v[60:63]
	s_waitcnt lgkmcnt(2)
	v_mfma_f32_16x16x32_bf16 v[60:63], v[120:123], v[56:59], v[86:89]
	s_waitcnt lgkmcnt(1)
	v_mfma_f32_16x16x32_bf16 v[70:73], v[124:127], v[56:59], v[90:93]
	s_waitcnt lgkmcnt(0)
	v_mfma_f32_16x16x32_bf16 v[56:59], v[128:131], v[56:59], v[64:67]
	ds_read2_b64 v[132:135], v11 offset0:24 offset1:28
	ds_read2_b64 v[136:139], v18 offset0:56 offset1:60
	ds_read2_b64 v[140:143], v68 offset0:88 offset1:92
	ds_read2_b64 v[144:147], v69 offset0:120 offset1:124
	v_mul_f32_e64 v48, v48, v10
	v_mul_f32_e64 v49, v49, v10
	v_pk_mul_f32 v[50:51], v[50:51], v[10:11] op_sel_hi:[1,0]
	v_pk_mul_f32 v[44:45], v[44:45], v[10:11] op_sel_hi:[1,0]
	v_pk_mul_f32 v[46:47], v[46:47], v[10:11] op_sel_hi:[1,0]
	v_bfe_u32 v19, v51, 16, 1
	v_bfe_u32 v64, v50, 16, 1
	v_bfe_u32 v65, v49, 16, 1
	v_bfe_u32 v66, v48, 16, 1
	v_add3_u32 v48, v48, v66, s33
	v_add3_u32 v49, v49, v65, s33
	v_add3_u32 v50, v50, v64, s33
	v_add3_u32 v19, v51, v19, s33
	v_bfe_u32 v51, v44, 16, 1
	v_bfe_u32 v64, v45, 16, 1
	v_bfe_u32 v65, v46, 16, 1
	v_bfe_u32 v66, v47, 16, 1
	v_add3_u32 v66, v47, v66, s33
	v_add3_u32 v65, v46, v65, s33
	v_add3_u32 v64, v45, v64, s33
	v_add3_u32 v51, v44, v51, s33
	v_lshrrev_b32_e32 v67, 16, v51
	v_lshrrev_b32_e32 v64, 16, v64
	v_lshrrev_b32_e32 v65, 16, v65
	v_lshrrev_b32_e32 v51, 16, v66
	v_and_or_b32 v51, v19, s29, v51
	v_and_or_b32 v50, v50, s29, v65
	v_and_or_b32 v49, v49, s29, v64
	v_and_or_b32 v48, v48, s29, v67
	s_waitcnt lgkmcnt(3)
	s_nop 1
	v_mfma_f32_16x16x32_bf16 v[44:47], v[132:135], v[48:51], v[52:55]
	s_waitcnt lgkmcnt(2)
	v_mfma_f32_16x16x32_bf16 v[52:55], v[136:139], v[48:51], v[60:63]
	s_waitcnt lgkmcnt(1)
	v_mfma_f32_16x16x32_bf16 v[60:63], v[140:143], v[48:51], v[70:73]
	s_waitcnt lgkmcnt(0)
	v_mfma_f32_16x16x32_bf16 v[48:51], v[144:147], v[48:51], v[56:59]
	ds_read2_b64 v[116:119], v11 offset0:32 offset1:36
	ds_read2_b64 v[120:123], v18 offset0:64 offset1:68
	ds_read2_b64 v[124:127], v68 offset0:96 offset1:100
	ds_read2_b64 v[128:131], v69 offset0:128 offset1:132
	v_mul_f32_e64 v40, v40, v10
	v_mul_f32_e64 v41, v41, v10
	v_pk_mul_f32 v[42:43], v[42:43], v[10:11] op_sel_hi:[1,0]
	v_pk_mul_f32 v[36:37], v[36:37], v[10:11] op_sel_hi:[1,0]
	v_pk_mul_f32 v[38:39], v[38:39], v[10:11] op_sel_hi:[1,0]
	v_bfe_u32 v19, v43, 16, 1
	v_bfe_u32 v56, v42, 16, 1
	v_bfe_u32 v57, v41, 16, 1
	v_bfe_u32 v58, v40, 16, 1
	v_add3_u32 v40, v40, v58, s33
	v_add3_u32 v41, v41, v57, s33
	v_add3_u32 v42, v42, v56, s33
	v_add3_u32 v19, v43, v19, s33
	v_bfe_u32 v43, v36, 16, 1
	v_bfe_u32 v56, v37, 16, 1
	v_bfe_u32 v57, v38, 16, 1
	v_bfe_u32 v58, v39, 16, 1
	v_add3_u32 v58, v39, v58, s33
	v_add3_u32 v57, v38, v57, s33
	v_add3_u32 v56, v37, v56, s33
	v_add3_u32 v43, v36, v43, s33
	v_lshrrev_b32_e32 v59, 16, v43
	v_lshrrev_b32_e32 v56, 16, v56
	v_lshrrev_b32_e32 v57, 16, v57
	v_lshrrev_b32_e32 v43, 16, v58
	v_and_or_b32 v43, v19, s29, v43
	v_and_or_b32 v42, v42, s29, v57
	v_and_or_b32 v41, v41, s29, v56
	v_and_or_b32 v40, v40, s29, v59
	s_waitcnt lgkmcnt(3)
	s_nop 1
	v_mfma_f32_16x16x32_bf16 v[36:39], v[116:119], v[40:43], v[44:47]
	s_waitcnt lgkmcnt(2)
	v_mfma_f32_16x16x32_bf16 v[44:47], v[120:123], v[40:43], v[52:55]
	s_waitcnt lgkmcnt(1)
	v_mfma_f32_16x16x32_bf16 v[52:55], v[124:127], v[40:43], v[60:63]
	s_waitcnt lgkmcnt(0)
	v_mfma_f32_16x16x32_bf16 v[40:43], v[128:131], v[40:43], v[48:51]
	ds_read2_b64 v[132:135], v11 offset0:40 offset1:44
	ds_read2_b64 v[136:139], v18 offset0:72 offset1:76
	ds_read2_b64 v[140:143], v68 offset0:104 offset1:108
	ds_read2_b64 v[144:147], v69 offset0:136 offset1:140
	v_mul_f32_e64 v32, v32, v10
	v_mul_f32_e64 v33, v33, v10
	v_pk_mul_f32 v[34:35], v[34:35], v[10:11] op_sel_hi:[1,0]
	v_pk_mul_f32 v[28:29], v[28:29], v[10:11] op_sel_hi:[1,0]
	v_pk_mul_f32 v[30:31], v[30:31], v[10:11] op_sel_hi:[1,0]
	v_bfe_u32 v19, v35, 16, 1
	v_bfe_u32 v48, v34, 16, 1
	v_bfe_u32 v49, v33, 16, 1
	v_bfe_u32 v50, v32, 16, 1
	v_add3_u32 v32, v32, v50, s33
	v_add3_u32 v33, v33, v49, s33
	v_add3_u32 v34, v34, v48, s33
	v_add3_u32 v19, v35, v19, s33
	v_bfe_u32 v35, v28, 16, 1
	v_bfe_u32 v48, v29, 16, 1
	v_bfe_u32 v49, v30, 16, 1
	v_bfe_u32 v50, v31, 16, 1
	v_add3_u32 v50, v31, v50, s33
	v_add3_u32 v49, v30, v49, s33
	v_add3_u32 v48, v29, v48, s33
	v_add3_u32 v35, v28, v35, s33
	v_lshrrev_b32_e32 v51, 16, v35
	v_lshrrev_b32_e32 v48, 16, v48
	v_lshrrev_b32_e32 v49, 16, v49
	v_lshrrev_b32_e32 v35, 16, v50
	v_and_or_b32 v35, v19, s29, v35
	v_and_or_b32 v34, v34, s29, v49
	v_and_or_b32 v33, v33, s29, v48
	v_and_or_b32 v32, v32, s29, v51
	s_waitcnt lgkmcnt(3)
	s_nop 1
	v_mfma_f32_16x16x32_bf16 v[28:31], v[132:135], v[32:35], v[36:39]
	s_waitcnt lgkmcnt(2)
	v_mfma_f32_16x16x32_bf16 v[36:39], v[136:139], v[32:35], v[44:47]
	s_waitcnt lgkmcnt(1)
	v_mfma_f32_16x16x32_bf16 v[44:47], v[140:143], v[32:35], v[52:55]
	s_waitcnt lgkmcnt(0)
	v_mfma_f32_16x16x32_bf16 v[32:35], v[144:147], v[32:35], v[40:43]
	ds_read2_b64 v[116:119], v11 offset0:48 offset1:52
	ds_read2_b64 v[120:123], v18 offset0:80 offset1:84
	ds_read2_b64 v[124:127], v68 offset0:112 offset1:116
	ds_read2_b64 v[128:131], v69 offset0:144 offset1:148
	v_mul_f32_e64 v24, v24, v10
	v_mul_f32_e64 v25, v25, v10
	v_pk_mul_f32 v[26:27], v[26:27], v[10:11] op_sel_hi:[1,0]
	v_pk_mul_f32 v[20:21], v[20:21], v[10:11] op_sel_hi:[1,0]
	v_pk_mul_f32 v[22:23], v[22:23], v[10:11] op_sel_hi:[1,0]
	v_bfe_u32 v19, v27, 16, 1
	v_bfe_u32 v40, v26, 16, 1
	v_bfe_u32 v41, v25, 16, 1
	v_bfe_u32 v42, v24, 16, 1
	v_add3_u32 v24, v24, v42, s33
	v_add3_u32 v25, v25, v41, s33
	v_add3_u32 v26, v26, v40, s33
	v_add3_u32 v19, v27, v19, s33
	v_bfe_u32 v27, v20, 16, 1
	v_bfe_u32 v40, v21, 16, 1
	v_bfe_u32 v41, v22, 16, 1
	v_bfe_u32 v42, v23, 16, 1
	v_add3_u32 v42, v23, v42, s33
	v_add3_u32 v41, v22, v41, s33
	v_add3_u32 v40, v21, v40, s33
	v_add3_u32 v27, v20, v27, s33
	v_lshrrev_b32_e32 v43, 16, v27
	v_lshrrev_b32_e32 v40, 16, v40
	v_lshrrev_b32_e32 v41, 16, v41
	v_lshrrev_b32_e32 v27, 16, v42
	v_and_or_b32 v27, v19, s29, v27
	v_and_or_b32 v26, v26, s29, v41
	v_and_or_b32 v25, v25, s29, v40
	v_and_or_b32 v24, v24, s29, v43
	s_waitcnt lgkmcnt(3)
	s_nop 1
	v_mfma_f32_16x16x32_bf16 v[20:23], v[116:119], v[24:27], v[28:31]
	s_waitcnt lgkmcnt(2)
	v_mfma_f32_16x16x32_bf16 v[28:31], v[120:123], v[24:27], v[36:39]
	s_waitcnt lgkmcnt(1)
	v_mfma_f32_16x16x32_bf16 v[36:39], v[124:127], v[24:27], v[44:47]
	s_waitcnt lgkmcnt(0)
	v_mfma_f32_16x16x32_bf16 v[24:27], v[128:131], v[24:27], v[32:35]
	ds_read2_b64 v[132:135], v11 offset0:56 offset1:60
	ds_read2_b64 v[136:139], v18 offset0:88 offset1:92
	ds_read2_b64 v[140:143], v68 offset0:120 offset1:124
	ds_read2_b64 v[144:147], v69 offset0:152 offset1:156
	v_mul_f32_e64 v16, v16, v10
	v_mul_f32_e64 v17, v17, v10
	v_pk_mul_f32 v[14:15], v[14:15], v[10:11] op_sel_hi:[1,0]
	v_pk_mul_f32 v[12:13], v[12:13], v[10:11] op_sel_hi:[1,0]
	v_pk_mul_f32 v[8:9], v[8:9], v[10:11] op_sel_hi:[1,0]
	v_bfe_u32 v10, v15, 16, 1
	v_bfe_u32 v32, v17, 16, 1
	v_bfe_u32 v33, v16, 16, 1
	v_add3_u32 v16, v16, v33, s33
	v_add3_u32 v17, v17, v32, s33
	v_add3_u32 v15, v15, v10, s33
	v_bfe_u32 v10, v12, 16, 1
	v_bfe_u32 v32, v8, 16, 1
	v_bfe_u32 v33, v9, 16, 1
	v_add3_u32 v33, v9, v33, s33
	v_add3_u32 v32, v8, v32, s33
	v_add3_u32 v12, v12, v10, s33
	v_bfe_u32 v19, v14, 16, 1
	v_add3_u32 v14, v14, v19, s33
	v_bfe_u32 v19, v13, 16, 1
	v_add3_u32 v13, v13, v19, s33
	v_lshrrev_b32_e32 v12, 16, v12
	v_lshrrev_b32_e32 v13, 16, v13
	v_lshrrev_b32_e32 v19, 16, v32
	v_lshrrev_b32_e32 v32, 16, v33
	v_and_or_b32 v35, v15, s29, v32
	v_and_or_b32 v34, v14, s29, v19
	v_and_or_b32 v33, v17, s29, v13
	v_and_or_b32 v32, v16, s29, v12
	s_waitcnt lgkmcnt(3)
	s_nop 1
	v_mfma_f32_16x16x32_bf16 v[20:23], v[132:135], v[32:35], v[20:23]
	s_waitcnt lgkmcnt(2)
	v_mfma_f32_16x16x32_bf16 v[16:19], v[136:139], v[32:35], v[28:31]
	s_waitcnt lgkmcnt(1)
	v_mfma_f32_16x16x32_bf16 v[12:15], v[140:143], v[32:35], v[36:39]
	s_waitcnt lgkmcnt(0)
	v_mfma_f32_16x16x32_bf16 v[8:11], v[144:147], v[32:35], v[24:27]
	s_and_saveexec_b64 s[2:3], s[0:1]
	s_cbranch_execz .LBB0_253
	s_nop 0
	v_bfe_u32 v26, v20, 16, 1
	v_add3_u32 v20, v20, v26, s33
	v_bfe_u32 v26, v21, 16, 1
	v_add3_u32 v21, v21, v26, s33
	v_lshrrev_b32_e32 v20, 16, v20
	v_add_u32_e32 v24, s6, v81
	v_and_or_b32 v20, v21, s29, v20
	v_bfe_u32 v21, v22, 16, 1
	v_ashrrev_i32_e32 v25, 31, v24
	v_add3_u32 v21, v22, v21, s33
	v_bfe_u32 v22, v23, 16, 1
	v_lshlrev_b64 v[24:25], 11, v[24:25]
	v_add3_u32 v22, v23, v22, s33
	v_lshrrev_b32_e32 v21, 16, v21
	v_lshl_add_u64 v[24:25], v[76:77], 0, v[24:25]
	v_and_or_b32 v21, v22, s29, v21
	global_store_dwordx2 v[24:25], v[20:21], off offset:1536
	v_bfe_u32 v20, v16, 16, 1
	v_add3_u32 v16, v16, v20, s33
	v_bfe_u32 v20, v17, 16, 1
	v_add3_u32 v17, v17, v20, s33
	v_lshrrev_b32_e32 v16, 16, v16
	v_and_or_b32 v16, v17, s29, v16
	v_bfe_u32 v17, v18, 16, 1
	v_add3_u32 v17, v18, v17, s33
	v_bfe_u32 v18, v19, 16, 1
	v_add3_u32 v18, v19, v18, s33
	v_lshrrev_b32_e32 v17, 16, v17
	v_and_or_b32 v17, v18, s29, v17
	global_store_dwordx2 v[24:25], v[16:17], off offset:1568
	v_bfe_u32 v16, v12, 16, 1
	v_add3_u32 v12, v12, v16, s33
	v_bfe_u32 v16, v13, 16, 1
	v_add3_u32 v13, v13, v16, s33
	v_lshrrev_b32_e32 v12, 16, v12
	v_and_or_b32 v12, v13, s29, v12
	v_bfe_u32 v13, v14, 16, 1
	v_add3_u32 v13, v14, v13, s33
	v_bfe_u32 v14, v15, 16, 1
	v_add3_u32 v14, v15, v14, s33
	v_lshrrev_b32_e32 v13, 16, v13
	v_and_or_b32 v13, v14, s29, v13
	global_store_dwordx2 v[24:25], v[12:13], off offset:1600
	v_bfe_u32 v12, v8, 16, 1
	v_add3_u32 v8, v8, v12, s33
	v_bfe_u32 v12, v9, 16, 1
	v_add3_u32 v9, v9, v12, s33
	v_lshrrev_b32_e32 v8, 16, v8
	v_and_or_b32 v8, v9, s29, v8
	v_bfe_u32 v9, v10, 16, 1
	v_add3_u32 v9, v10, v9, s33
	v_bfe_u32 v10, v11, 16, 1
	v_add3_u32 v10, v11, v10, s33
	v_lshrrev_b32_e32 v9, 16, v9
	v_and_or_b32 v9, v10, s29, v9
	global_store_dwordx2 v[24:25], v[8:9], off offset:1632
	s_branch .LBB0_253
